# FFN-in epilogue: conv-constant/scale loads issued at epilogue top (removes 5 serialized waits per tile) + earlier hoists
# baseline (speedup 1.0000x reference)
.LBB0_1876:
	ds_read_b128 v[130:133], v219
	ds_read_b128 v[134:137], v219 offset:1024
	ds_read_b128 v[138:141], v219 offset:2048
	ds_read_b128 v[142:145], v219 offset:3072
	ds_read_b128 v[146:149], v220
	ds_read_b128 v[150:153], v220 offset:1024
	ds_read_b128 v[154:157], v220 offset:2048
	ds_read_b128 v[158:161], v220 offset:3072
	s_add_u32 s44, s42, 0xfff80080
	s_addc_u32 s45, s43, -1
	s_cmp_eq_u32 s74, 28
	s_cselect_b32 s47, s31, s45
	s_cselect_b32 s46, s33, s44
	s_cselect_b32 s45, s29, s73
	s_cselect_b32 s44, s39, s41
	v_lshl_add_u64 v[178:179], s[42:43], 0, v[198:199]
	s_add_i32 m0, s51, 0xc000
	ds_read_b128 v[162:165], v221
	ds_read_b128 v[166:169], v221 offset:1024
	ds_read_b128 v[170:173], v221 offset:2048
	ds_read_b128 v[174:177], v221 offset:3072
	ds_read_b128 v[206:209], v221 offset:4096
	ds_read_b128 v[210:213], v221 offset:5120
	ds_read_b128 v[224:227], v221 offset:6144
	ds_read_b128 v[228:231], v221 offset:7168
	global_load_lds_dwordx4 v[178:179], off
	v_lshl_add_u64 v[178:179], s[42:43], 0, v[200:201]
	s_add_i32 m0, s51, 0xe000
	s_nop 0
	global_load_lds_dwordx4 v[178:179], off
	s_waitcnt vmcnt(8)
	s_waitcnt lgkmcnt(0)
	s_barrier
	s_setprio 1
	s_waitcnt lgkmcnt(0)
	v_mfma_i32_16x16x64_i8 v[126:129], v[130:133], v[162:165], v[126:129]
	v_mfma_i32_16x16x64_i8 v[62:65], v[138:141], v[162:165], v[62:65]
	v_mfma_i32_16x16x64_i8 v[118:121], v[130:133], v[170:173], v[118:121]
	v_mfma_i32_16x16x64_i8 v[54:57], v[138:141], v[170:173], v[54:57]
	v_mfma_i32_16x16x64_i8 v[110:113], v[130:133], v[206:209], v[110:113]
	v_mfma_i32_16x16x64_i8 v[46:49], v[138:141], v[206:209], v[46:49]
	v_mfma_i32_16x16x64_i8 v[102:105], v[130:133], v[224:227], v[102:105]
	v_mfma_i32_16x16x64_i8 v[38:41], v[138:141], v[224:227], v[38:41]
	v_mfma_i32_16x16x64_i8 v[126:129], v[134:137], v[166:169], v[126:129]
	v_mfma_i32_16x16x64_i8 v[62:65], v[142:145], v[166:169], v[62:65]
	v_mfma_i32_16x16x64_i8 v[118:121], v[134:137], v[174:177], v[118:121]
	v_mfma_i32_16x16x64_i8 v[54:57], v[142:145], v[174:177], v[54:57]
	v_mfma_i32_16x16x64_i8 v[110:113], v[134:137], v[210:213], v[110:113]
	v_mfma_i32_16x16x64_i8 v[46:49], v[142:145], v[210:213], v[46:49]
	v_mfma_i32_16x16x64_i8 v[102:105], v[134:137], v[228:231], v[102:105]
	v_mfma_i32_16x16x64_i8 v[38:41], v[142:145], v[228:231], v[38:41]
	s_setprio 0
	s_setprio 1
	v_mfma_i32_16x16x64_i8 v[122:125], v[146:149], v[162:165], v[122:125]
	v_mfma_i32_16x16x64_i8 v[58:61], v[154:157], v[162:165], v[58:61]
	v_mfma_i32_16x16x64_i8 v[114:117], v[146:149], v[170:173], v[114:117]
	v_mfma_i32_16x16x64_i8 v[50:53], v[154:157], v[170:173], v[50:53]
	v_mfma_i32_16x16x64_i8 v[106:109], v[146:149], v[206:209], v[106:109]
	v_mfma_i32_16x16x64_i8 v[42:45], v[154:157], v[206:209], v[42:45]
	v_mfma_i32_16x16x64_i8 v[98:101], v[146:149], v[224:227], v[98:101]
	v_mfma_i32_16x16x64_i8 v[34:37], v[154:157], v[224:227], v[34:37]
	v_mfma_i32_16x16x64_i8 v[122:125], v[150:153], v[166:169], v[122:125]
	v_mfma_i32_16x16x64_i8 v[58:61], v[158:161], v[166:169], v[58:61]
	v_mfma_i32_16x16x64_i8 v[114:117], v[150:153], v[174:177], v[114:117]
	v_mfma_i32_16x16x64_i8 v[50:53], v[158:161], v[174:177], v[50:53]
	v_mfma_i32_16x16x64_i8 v[106:109], v[150:153], v[210:213], v[106:109]
	v_mfma_i32_16x16x64_i8 v[42:45], v[158:161], v[210:213], v[42:45]
	v_mfma_i32_16x16x64_i8 v[98:101], v[150:153], v[228:231], v[98:101]
	v_mfma_i32_16x16x64_i8 v[34:37], v[158:161], v[228:231], v[34:37]
	s_setprio 0
	s_barrier
	s_add_i32 s75, s69, s50
	v_lshl_add_u64 v[178:179], s[44:45], 0, v[182:183]
	s_mov_b32 m0, s75
	ds_read_b128 v[162:165], v221 offset:16384
	ds_read_b128 v[166:169], v221 offset:17408
	ds_read_b128 v[170:173], v221 offset:18432
	ds_read_b128 v[174:177], v221 offset:19456
	ds_read_b128 v[206:209], v221 offset:20480
	ds_read_b128 v[210:213], v221 offset:21504
	ds_read_b128 v[224:227], v221 offset:22528
	ds_read_b128 v[228:231], v221 offset:23552
	global_load_lds_dwordx4 v[178:179], off
	s_add_i32 m0, s75, 0x2000
	s_add_u32 s76, s44, 0x80000
	v_lshl_add_u64 v[232:233], s[44:45], 0, v[186:187]
	s_addc_u32 s77, s45, 0
	s_add_i32 s75, s70, s50
	global_load_lds_dwordx4 v[232:233], off
	v_lshl_add_u64 v[234:235], s[76:77], 0, v[182:183]
	s_mov_b32 m0, s75
	v_lshl_add_u64 v[236:237], s[46:47], 0, v[184:185]
	global_load_lds_dwordx4 v[234:235], off
	v_lshl_add_u64 v[234:235], s[76:77], 0, v[186:187]
	s_add_i32 m0, s75, 0x2000
	s_nop 0
	global_load_lds_dwordx4 v[234:235], off
	v_lshl_add_u64 v[234:235], s[46:47], 0, v[180:181]
	s_mov_b32 m0, s51
	s_nop 0
	global_load_lds_dwordx4 v[234:235], off
	s_mov_b32 m0, s52
	s_nop 0
	global_load_lds_dwordx4 v[236:237], off
	s_waitcnt vmcnt(8)
	s_waitcnt lgkmcnt(0)
	s_barrier
	s_setprio 1
	s_waitcnt lgkmcnt(0)
	v_mfma_i32_16x16x64_i8 v[94:97], v[130:133], v[162:165], v[94:97]
	v_mfma_i32_16x16x64_i8 v[30:33], v[138:141], v[162:165], v[30:33]
	v_mfma_i32_16x16x64_i8 v[86:89], v[130:133], v[170:173], v[86:89]
	v_mfma_i32_16x16x64_i8 v[22:25], v[138:141], v[170:173], v[22:25]
	v_mfma_i32_16x16x64_i8 v[78:81], v[130:133], v[206:209], v[78:81]
	v_mfma_i32_16x16x64_i8 v[14:17], v[138:141], v[206:209], v[14:17]
	v_mfma_i32_16x16x64_i8 v[70:73], v[130:133], v[224:227], v[70:73]
	v_mfma_i32_16x16x64_i8 v[6:9], v[138:141], v[224:227], v[6:9]
	v_mfma_i32_16x16x64_i8 v[94:97], v[134:137], v[166:169], v[94:97]
	v_mfma_i32_16x16x64_i8 v[30:33], v[142:145], v[166:169], v[30:33]
	v_mfma_i32_16x16x64_i8 v[86:89], v[134:137], v[174:177], v[86:89]
	v_mfma_i32_16x16x64_i8 v[22:25], v[142:145], v[174:177], v[22:25]
	v_mfma_i32_16x16x64_i8 v[78:81], v[134:137], v[210:213], v[78:81]
	v_mfma_i32_16x16x64_i8 v[14:17], v[142:145], v[210:213], v[14:17]
	v_mfma_i32_16x16x64_i8 v[70:73], v[134:137], v[228:231], v[70:73]
	v_mfma_i32_16x16x64_i8 v[6:9], v[142:145], v[228:231], v[6:9]
	s_setprio 0
	s_setprio 1
	v_mfma_i32_16x16x64_i8 v[90:93], v[146:149], v[162:165], v[90:93]
	v_mfma_i32_16x16x64_i8 v[26:29], v[154:157], v[162:165], v[26:29]
	v_mfma_i32_16x16x64_i8 v[82:85], v[146:149], v[170:173], v[82:85]
	v_mfma_i32_16x16x64_i8 v[18:21], v[154:157], v[170:173], v[18:21]
	v_mfma_i32_16x16x64_i8 v[74:77], v[146:149], v[206:209], v[74:77]
	v_mfma_i32_16x16x64_i8 v[10:13], v[154:157], v[206:209], v[10:13]
	v_mfma_i32_16x16x64_i8 v[66:69], v[146:149], v[224:227], v[66:69]
	v_mfma_i32_16x16x64_i8 v[2:5], v[154:157], v[224:227], v[2:5]
	v_mfma_i32_16x16x64_i8 v[90:93], v[150:153], v[166:169], v[90:93]
	v_mfma_i32_16x16x64_i8 v[26:29], v[158:161], v[166:169], v[26:29]
	v_mfma_i32_16x16x64_i8 v[82:85], v[150:153], v[174:177], v[82:85]
	v_mfma_i32_16x16x64_i8 v[18:21], v[158:161], v[174:177], v[18:21]
	v_mfma_i32_16x16x64_i8 v[74:77], v[150:153], v[210:213], v[74:77]
	v_mfma_i32_16x16x64_i8 v[10:13], v[158:161], v[210:213], v[10:13]
	v_mfma_i32_16x16x64_i8 v[66:69], v[150:153], v[228:231], v[66:69]
	v_mfma_i32_16x16x64_i8 v[2:5], v[158:161], v[228:231], v[2:5]
	s_setprio 0
	s_barrier
	s_add_i32 s75, 0, 0x18000
	s_add_i32 s76, 0, 0x1c000
	v_add_u32_e32 v142, s75, v191
	v_add_u32_e32 v158, s76, v191
	ds_read_b128 v[130:133], v142
	ds_read_b128 v[134:137], v142 offset:1024
	ds_read_b128 v[138:141], v142 offset:2048
	ds_read_b128 v[142:145], v142 offset:3072
	ds_read_b128 v[146:149], v158
	ds_read_b128 v[150:153], v158 offset:1024
	ds_read_b128 v[154:157], v158 offset:2048
	ds_read_b128 v[158:161], v158 offset:3072
	s_add_u32 s46, s46, 0x80000
	s_addc_u32 s47, s47, 0
	s_mov_b32 m0, s53
	v_lshl_add_u64 v[238:239], s[46:47], 0, v[180:181]
	ds_read_b128 v[162:165], v221 offset:32768
	ds_read_b128 v[166:169], v221 offset:33792
	ds_read_b128 v[170:173], v221 offset:34816
	ds_read_b128 v[174:177], v221 offset:35840
	ds_read_b128 v[206:209], v221 offset:36864
	ds_read_b128 v[210:213], v221 offset:37888
	ds_read_b128 v[224:227], v221 offset:38912
	ds_read_b128 v[228:231], v221 offset:39936
	global_load_lds_dwordx4 v[238:239], off
	v_lshl_add_u64 v[238:239], s[46:47], 0, v[184:185]
	s_mov_b32 m0, s54
	s_nop 0
	global_load_lds_dwordx4 v[238:239], off
	s_waitcnt vmcnt(8)
	s_waitcnt lgkmcnt(0)
	s_barrier
	s_setprio 1
	s_waitcnt lgkmcnt(0)
	v_mfma_i32_16x16x64_i8 v[126:129], v[130:133], v[162:165], v[126:129]
	v_mfma_i32_16x16x64_i8 v[62:65], v[138:141], v[162:165], v[62:65]
	v_mfma_i32_16x16x64_i8 v[118:121], v[130:133], v[170:173], v[118:121]
	v_mfma_i32_16x16x64_i8 v[54:57], v[138:141], v[170:173], v[54:57]
	v_mfma_i32_16x16x64_i8 v[110:113], v[130:133], v[206:209], v[110:113]
	v_mfma_i32_16x16x64_i8 v[46:49], v[138:141], v[206:209], v[46:49]
	v_mfma_i32_16x16x64_i8 v[102:105], v[130:133], v[224:227], v[102:105]
	v_mfma_i32_16x16x64_i8 v[38:41], v[138:141], v[224:227], v[38:41]
	v_mfma_i32_16x16x64_i8 v[126:129], v[134:137], v[166:169], v[126:129]
	v_mfma_i32_16x16x64_i8 v[62:65], v[142:145], v[166:169], v[62:65]
	v_mfma_i32_16x16x64_i8 v[118:121], v[134:137], v[174:177], v[118:121]
	v_mfma_i32_16x16x64_i8 v[54:57], v[142:145], v[174:177], v[54:57]
	v_mfma_i32_16x16x64_i8 v[110:113], v[134:137], v[210:213], v[110:113]
	v_mfma_i32_16x16x64_i8 v[46:49], v[142:145], v[210:213], v[46:49]
	v_mfma_i32_16x16x64_i8 v[102:105], v[134:137], v[228:231], v[102:105]
	v_mfma_i32_16x16x64_i8 v[38:41], v[142:145], v[228:231], v[38:41]
	s_setprio 0
	s_setprio 1
	v_mfma_i32_16x16x64_i8 v[122:125], v[146:149], v[162:165], v[122:125]
	v_mfma_i32_16x16x64_i8 v[58:61], v[154:157], v[162:165], v[58:61]
	v_mfma_i32_16x16x64_i8 v[114:117], v[146:149], v[170:173], v[114:117]
	v_mfma_i32_16x16x64_i8 v[50:53], v[154:157], v[170:173], v[50:53]
	v_mfma_i32_16x16x64_i8 v[106:109], v[146:149], v[206:209], v[106:109]
	v_mfma_i32_16x16x64_i8 v[42:45], v[154:157], v[206:209], v[42:45]
	v_mfma_i32_16x16x64_i8 v[98:101], v[146:149], v[224:227], v[98:101]
	v_mfma_i32_16x16x64_i8 v[34:37], v[154:157], v[224:227], v[34:37]
	v_mfma_i32_16x16x64_i8 v[122:125], v[150:153], v[166:169], v[122:125]
	v_mfma_i32_16x16x64_i8 v[58:61], v[158:161], v[166:169], v[58:61]
	v_mfma_i32_16x16x64_i8 v[114:117], v[150:153], v[174:177], v[114:117]
	v_mfma_i32_16x16x64_i8 v[50:53], v[158:161], v[174:177], v[50:53]
	v_mfma_i32_16x16x64_i8 v[106:109], v[150:153], v[210:213], v[106:109]
	v_mfma_i32_16x16x64_i8 v[42:45], v[158:161], v[210:213], v[42:45]
	v_mfma_i32_16x16x64_i8 v[98:101], v[150:153], v[228:231], v[98:101]
	v_mfma_i32_16x16x64_i8 v[34:37], v[158:161], v[228:231], v[34:37]
	s_setprio 0
	s_barrier
	s_add_i32 s46, s75, s50
	v_lshl_add_u64 v[178:179], v[178:179], 0, s[18:19]
	s_mov_b32 m0, s46
	ds_read_b128 v[162:165], v221 offset:49152
	ds_read_b128 v[166:169], v221 offset:50176
	ds_read_b128 v[170:173], v221 offset:51200
	ds_read_b128 v[174:177], v221 offset:52224
	ds_read_b128 v[206:209], v221 offset:53248
	ds_read_b128 v[210:213], v221 offset:54272
	ds_read_b128 v[224:227], v221 offset:55296
	ds_read_b128 v[228:231], v221 offset:56320
	global_load_lds_dwordx4 v[178:179], off
	s_add_i32 m0, s46, 0x2000
	s_add_u32 s44, s44, 0x80080
	v_lshl_add_u64 v[178:179], v[232:233], 0, s[18:19]
	s_addc_u32 s45, s45, 0
	s_add_i32 s46, s76, s50
	global_load_lds_dwordx4 v[178:179], off
	v_lshl_add_u64 v[178:179], s[44:45], 0, v[182:183]
	s_mov_b32 m0, s46
	s_nop 0
	global_load_lds_dwordx4 v[178:179], off
	v_lshl_add_u64 v[178:179], s[44:45], 0, v[186:187]
	s_add_i32 m0, s46, 0x2000
	s_nop 0
	global_load_lds_dwordx4 v[178:179], off
	v_lshl_add_u64 v[178:179], v[234:235], 0, s[18:19]
	s_mov_b32 m0, s61
	s_nop 0
	global_load_lds_dwordx4 v[178:179], off
	v_lshl_add_u64 v[178:179], v[236:237], 0, s[18:19]
	s_mov_b32 m0, s68
	s_nop 0
	global_load_lds_dwordx4 v[178:179], off
	s_waitcnt vmcnt(8)
	s_waitcnt lgkmcnt(0)
	s_barrier
	s_setprio 1
	s_waitcnt lgkmcnt(0)
	v_mfma_i32_16x16x64_i8 v[94:97], v[130:133], v[162:165], v[94:97]
	v_mfma_i32_16x16x64_i8 v[30:33], v[138:141], v[162:165], v[30:33]
	v_mfma_i32_16x16x64_i8 v[86:89], v[130:133], v[170:173], v[86:89]
	v_mfma_i32_16x16x64_i8 v[22:25], v[138:141], v[170:173], v[22:25]
	v_mfma_i32_16x16x64_i8 v[78:81], v[130:133], v[206:209], v[78:81]
	v_mfma_i32_16x16x64_i8 v[14:17], v[138:141], v[206:209], v[14:17]
	v_mfma_i32_16x16x64_i8 v[70:73], v[130:133], v[224:227], v[70:73]
	v_mfma_i32_16x16x64_i8 v[6:9], v[138:141], v[224:227], v[6:9]
	v_mfma_i32_16x16x64_i8 v[94:97], v[134:137], v[166:169], v[94:97]
	v_mfma_i32_16x16x64_i8 v[30:33], v[142:145], v[166:169], v[30:33]
	v_mfma_i32_16x16x64_i8 v[86:89], v[134:137], v[174:177], v[86:89]
	v_mfma_i32_16x16x64_i8 v[22:25], v[142:145], v[174:177], v[22:25]
	v_mfma_i32_16x16x64_i8 v[78:81], v[134:137], v[210:213], v[78:81]
	v_mfma_i32_16x16x64_i8 v[14:17], v[142:145], v[210:213], v[14:17]
	v_mfma_i32_16x16x64_i8 v[70:73], v[134:137], v[228:231], v[70:73]
	v_mfma_i32_16x16x64_i8 v[6:9], v[142:145], v[228:231], v[6:9]
	s_setprio 0
	s_setprio 1
	v_mfma_i32_16x16x64_i8 v[90:93], v[146:149], v[162:165], v[90:93]
	v_mfma_i32_16x16x64_i8 v[26:29], v[154:157], v[162:165], v[26:29]
	v_mfma_i32_16x16x64_i8 v[82:85], v[146:149], v[170:173], v[82:85]
	v_mfma_i32_16x16x64_i8 v[18:21], v[154:157], v[170:173], v[18:21]
	v_mfma_i32_16x16x64_i8 v[74:77], v[146:149], v[206:209], v[74:77]
	v_mfma_i32_16x16x64_i8 v[10:13], v[154:157], v[206:209], v[10:13]
	v_mfma_i32_16x16x64_i8 v[66:69], v[146:149], v[224:227], v[66:69]
	v_mfma_i32_16x16x64_i8 v[2:5], v[154:157], v[224:227], v[2:5]
	v_mfma_i32_16x16x64_i8 v[90:93], v[150:153], v[166:169], v[90:93]
	v_mfma_i32_16x16x64_i8 v[26:29], v[158:161], v[166:169], v[26:29]
	v_mfma_i32_16x16x64_i8 v[82:85], v[150:153], v[174:177], v[82:85]
	v_mfma_i32_16x16x64_i8 v[18:21], v[158:161], v[174:177], v[18:21]
	v_mfma_i32_16x16x64_i8 v[74:77], v[150:153], v[210:213], v[74:77]
	v_mfma_i32_16x16x64_i8 v[10:13], v[158:161], v[210:213], v[10:13]
	v_mfma_i32_16x16x64_i8 v[66:69], v[150:153], v[228:231], v[66:69]
	v_mfma_i32_16x16x64_i8 v[2:5], v[158:161], v[228:231], v[2:5]
	s_setprio 0
	s_barrier
	s_add_i32 s74, s74, 2
	s_add_u32 s42, s42, 0x100
	s_addc_u32 s43, s43, 0
	s_add_u32 s41, s41, 0x100
	s_addc_u32 s73, s73, 0
	s_cmp_gt_u32 s74, 29
	s_cbranch_scc0 .LBB0_1876
	s_load_dword s94, s[16:17], 0x0
	v_lshl_or_b32 v248, s40, 7, v194
	v_mov_b32_e32 v249, 0
	s_lshl_b32 s96, s40, 10
	s_mov_b32 s97, 0
	v_lshlrev_b64 v[248:249], 2, v[248:249]
	v_lshl_add_u64 v[244:245], v[196:197], 0, s[96:97]
	v_lshl_add_u64 v[240:241], s[56:57], 0, v[248:249]
	v_lshl_add_u64 v[242:243], s[58:59], 0, v[248:249]
	global_load_dwordx4 v[176:179], v[244:245], off
	global_load_dwordx4 v[232:235], v[244:245], off offset:16
	global_load_dwordx4 v[160:163], v[244:245], off offset:512
	global_load_dwordx4 v[236:239], v[244:245], off offset:528
	global_load_dwordx4 v[224:227], v[242:243], off
	global_load_dwordx4 v[148:151], v[240:241], off
	s_mov_b32 s96, 0xac00
	v_lshl_add_u64 v[246:247], v[242:243], 0, s[96:97]
	global_load_dwordx4 v[228:231], v[246:247], off
	s_mov_b32 s96, 0xac00
	v_lshl_add_u64 v[246:247], v[240:241], 0, s[96:97]
	global_load_dwordx4 v[168:171], v[246:247], off
	s_mov_b32 s96, 0x15800
	v_lshl_add_u64 v[246:247], v[240:241], 0, s[96:97]
	global_load_dwordx4 v[156:159], v[246:247], off
	s_mov_b32 s96, 0x20400
	v_lshl_add_u64 v[246:247], v[240:241], 0, s[96:97]
	global_load_dwordx4 v[164:167], v[246:247], off
	s_mov_b32 s96, 0x2b000
	v_lshl_add_u64 v[246:247], v[240:241], 0, s[96:97]
	global_load_dwordx4 v[152:155], v[246:247], off
	s_mov_b32 s96, 0x35c00
	v_lshl_add_u64 v[246:247], v[240:241], 0, s[96:97]
	global_load_dwordx4 v[172:175], v[246:247], off
	s_and_b64 vcc, exec, s[20:21]
	s_cbranch_vccz .LBB0_1879
	s_barrier
.LBB0_1879:
	s_nop 15
	s_nop 15
	s_waitcnt lgkmcnt(0)
	v_cvt_f32_i32 v126, v126
	v_cvt_f32_i32 v127, v127
	v_cvt_f32_i32 v128, v128
	v_cvt_f32_i32 v129, v129
	v_cvt_f32_i32 v62, v62
	v_cvt_f32_i32 v63, v63
	v_cvt_f32_i32 v64, v64
	v_cvt_f32_i32 v65, v65
	v_cvt_f32_i32 v118, v118
	v_cvt_f32_i32 v119, v119
	v_cvt_f32_i32 v120, v120
	v_cvt_f32_i32 v121, v121
	v_cvt_f32_i32 v54, v54
	v_cvt_f32_i32 v55, v55
	v_cvt_f32_i32 v56, v56
	v_cvt_f32_i32 v57, v57
	v_cvt_f32_i32 v110, v110
	v_cvt_f32_i32 v111, v111
	v_cvt_f32_i32 v112, v112
	v_cvt_f32_i32 v113, v113
	v_cvt_f32_i32 v46, v46
	v_cvt_f32_i32 v47, v47
	v_cvt_f32_i32 v48, v48
	v_cvt_f32_i32 v49, v49
	v_cvt_f32_i32 v102, v102
	v_cvt_f32_i32 v103, v103
	v_cvt_f32_i32 v104, v104
	v_cvt_f32_i32 v105, v105
	v_cvt_f32_i32 v38, v38
	v_cvt_f32_i32 v39, v39
	v_cvt_f32_i32 v40, v40
	v_cvt_f32_i32 v41, v41
	v_cvt_f32_i32 v122, v122
	v_cvt_f32_i32 v123, v123
	v_cvt_f32_i32 v124, v124
	v_cvt_f32_i32 v125, v125
	v_cvt_f32_i32 v58, v58
	v_cvt_f32_i32 v59, v59
	v_cvt_f32_i32 v60, v60
	v_cvt_f32_i32 v61, v61
	v_cvt_f32_i32 v114, v114
	v_cvt_f32_i32 v115, v115
	v_cvt_f32_i32 v116, v116
	v_cvt_f32_i32 v117, v117
	v_cvt_f32_i32 v50, v50
	v_cvt_f32_i32 v51, v51
	v_cvt_f32_i32 v52, v52
	v_cvt_f32_i32 v53, v53
	v_cvt_f32_i32 v106, v106
	v_cvt_f32_i32 v107, v107
	v_cvt_f32_i32 v108, v108
	v_cvt_f32_i32 v109, v109
	v_cvt_f32_i32 v42, v42
	v_cvt_f32_i32 v43, v43
	v_cvt_f32_i32 v44, v44
	v_cvt_f32_i32 v45, v45
	v_cvt_f32_i32 v98, v98
	v_cvt_f32_i32 v99, v99
	v_cvt_f32_i32 v100, v100
	v_cvt_f32_i32 v101, v101
	v_cvt_f32_i32 v34, v34
	v_cvt_f32_i32 v35, v35
	v_cvt_f32_i32 v36, v36
	v_cvt_f32_i32 v37, v37
	v_cvt_f32_i32 v94, v94
	v_cvt_f32_i32 v95, v95
	v_cvt_f32_i32 v96, v96
	v_cvt_f32_i32 v97, v97
	v_cvt_f32_i32 v30, v30
	v_cvt_f32_i32 v31, v31
	v_cvt_f32_i32 v32, v32
	v_cvt_f32_i32 v33, v33
	v_cvt_f32_i32 v86, v86
	v_cvt_f32_i32 v87, v87
	v_cvt_f32_i32 v88, v88
	v_cvt_f32_i32 v89, v89
	v_cvt_f32_i32 v22, v22
	v_cvt_f32_i32 v23, v23
	v_cvt_f32_i32 v24, v24
	v_cvt_f32_i32 v25, v25
	v_cvt_f32_i32 v78, v78
	v_cvt_f32_i32 v79, v79
	v_cvt_f32_i32 v80, v80
	v_cvt_f32_i32 v81, v81
	v_cvt_f32_i32 v14, v14
	v_cvt_f32_i32 v15, v15
	v_cvt_f32_i32 v16, v16
	v_cvt_f32_i32 v17, v17
	v_cvt_f32_i32 v70, v70
	v_cvt_f32_i32 v71, v71
	v_cvt_f32_i32 v72, v72
	v_cvt_f32_i32 v73, v73
	v_cvt_f32_i32 v6, v6
	v_cvt_f32_i32 v7, v7
	v_cvt_f32_i32 v8, v8
	v_cvt_f32_i32 v9, v9
	v_cvt_f32_i32 v90, v90
	v_cvt_f32_i32 v91, v91
	v_cvt_f32_i32 v92, v92
	v_cvt_f32_i32 v93, v93
	v_cvt_f32_i32 v26, v26
	v_cvt_f32_i32 v27, v27
	v_cvt_f32_i32 v28, v28
	v_cvt_f32_i32 v29, v29
	v_cvt_f32_i32 v82, v82
	v_cvt_f32_i32 v83, v83
	v_cvt_f32_i32 v84, v84
	v_cvt_f32_i32 v85, v85
	v_cvt_f32_i32 v18, v18
	v_cvt_f32_i32 v19, v19
	v_cvt_f32_i32 v20, v20
	v_cvt_f32_i32 v21, v21
	v_cvt_f32_i32 v74, v74
	v_cvt_f32_i32 v75, v75
	v_cvt_f32_i32 v76, v76
	v_cvt_f32_i32 v77, v77
	v_cvt_f32_i32 v10, v10
	v_cvt_f32_i32 v11, v11
	v_cvt_f32_i32 v12, v12
	v_cvt_f32_i32 v13, v13
	v_cvt_f32_i32 v66, v66
	v_cvt_f32_i32 v67, v67
	v_cvt_f32_i32 v68, v68
	v_cvt_f32_i32 v69, v69
	v_cvt_f32_i32 v2, v2
	v_cvt_f32_i32 v3, v3
	v_cvt_f32_i32 v4, v4
	v_cvt_f32_i32 v5, v5
	s_waitcnt vmcnt(0)
	s_and_saveexec_b64 s[42:43], s[4:5]
	s_cbranch_execz .LBB0_1881
	ds_write_b128 v195, v[102:105]
	ds_write_b128 v195, v[38:41] offset:16
	ds_write_b128 v195, v[98:101] offset:512
	ds_write_b128 v195, v[34:37] offset:528
	ds_write_b128 v214, v[70:73]
	ds_write_b128 v195, v[6:9] offset:4112
	ds_write_b128 v195, v[66:69] offset:4608
	ds_write_b128 v195, v[2:5] offset:4624
	s_or_b64 exec, exec, s[42:43]
	s_and_saveexec_b64 s[42:43], s[22:23]
	s_cbranch_execz .LBB0_1883
	s_branch .LBB0_1882

.LBB0_1882:
	s_lshl_b32 s44, s40, 8
	s_ashr_i32 s45, s44, 31
	s_lshl_b64 s[44:45], s[44:45], 2
	v_lshl_add_u64 v[138:139], v[196:197], 0, s[44:45]
	s_nop 1
	v_mov_b32_e32 v140, s94
	s_nop 1
	v_mov_b32_e32 v130, v176
	v_mov_b32_e32 v131, v177
	v_mov_b32_e32 v132, v178
	v_mov_b32_e32 v133, v179
	s_nop 1
	v_mov_b32_e32 v134, v232
	v_mov_b32_e32 v135, v233
	v_mov_b32_e32 v136, v234
	v_mov_b32_e32 v137, v235
	s_ashr_i32 s39, s38, 31
	s_lshl_b64 s[46:47], s[38:39], 2
	v_mov_b64_e32 v[142:143], s[14:15]
	v_or_b32_e32 v141, s46, v190
	v_mad_u64_u32 v[142:143], s[74:75], v141, s71, v[142:143]
	v_mad_i32_i24 v143, s47, v222, v143
	v_lshlrev_b32_e32 v188, 2, v194
	v_lshl_add_u64 v[142:143], v[142:143], 0, s[44:45]
	v_lshl_add_u64 v[142:143], v[142:143], 0, v[188:189]
	s_nop 0
	v_pk_mul_f32 v[132:133], v[132:133], v[140:141] op_sel_hi:[1,0]
	v_pk_mul_f32 v[130:131], v[130:131], v[140:141] op_sel_hi:[1,0]
	v_pk_mul_f32 v[132:133], v[128:129], v[132:133]
	v_pk_mul_f32 v[130:131], v[126:127], v[130:131]
	global_store_dwordx4 v[142:143], v[130:133], off
	s_nop 1
	v_mov_b32_e32 v130, s94
	s_nop 0
	v_pk_mul_f32 v[132:133], v[136:137], v[130:131] op_sel_hi:[1,0]
	v_pk_mul_f32 v[130:131], v[134:135], v[130:131] op_sel_hi:[1,0]
	v_pk_mul_f32 v[132:133], v[64:65], v[132:133]
	v_pk_mul_f32 v[130:131], v[62:63], v[130:131]
	global_store_dwordx4 v[142:143], v[130:133], off offset:16
	s_nop 1
	v_mov_b32_e32 v140, s94
	s_nop 0
	s_nop 1
	v_mov_b32_e32 v130, v160
	v_mov_b32_e32 v131, v161
	v_mov_b32_e32 v132, v162
	v_mov_b32_e32 v133, v163
	s_nop 1
	v_mov_b32_e32 v134, v236
	v_mov_b32_e32 v135, v237
	v_mov_b32_e32 v136, v238
	v_mov_b32_e32 v137, v239
	s_nop 0
	v_pk_mul_f32 v[132:133], v[132:133], v[140:141] op_sel_hi:[1,0]
	v_pk_mul_f32 v[130:131], v[130:131], v[140:141] op_sel_hi:[1,0]
	v_pk_mul_f32 v[132:133], v[124:125], v[132:133]
	v_pk_mul_f32 v[130:131], v[122:123], v[130:131]
	global_store_dwordx4 v[142:143], v[130:133], off offset:512
	s_nop 1
	v_mov_b32_e32 v130, s94
	s_nop 0
	v_pk_mul_f32 v[132:133], v[136:137], v[130:131] op_sel_hi:[1,0]
	v_pk_mul_f32 v[130:131], v[134:135], v[130:131] op_sel_hi:[1,0]
	v_pk_mul_f32 v[132:133], v[60:61], v[132:133]
	v_pk_mul_f32 v[130:131], v[58:59], v[130:131]
	global_store_dwordx4 v[142:143], v[130:133], off offset:528

.LBB0_1886:
	s_lshl_b32 s44, s40, 8
	s_ashr_i32 s45, s44, 31
	s_lshl_b64 s[46:47], s[44:45], 2
	v_lshl_add_u64 v[138:139], v[196:197], 0, s[46:47]
	s_nop 1
	v_mov_b32_e32 v140, s94
	s_nop 1
	v_mov_b32_e32 v130, v176
	v_mov_b32_e32 v131, v177
	v_mov_b32_e32 v132, v178
	v_mov_b32_e32 v133, v179
	s_nop 1
	v_mov_b32_e32 v134, v232
	v_mov_b32_e32 v135, v233
	v_mov_b32_e32 v136, v234
	v_mov_b32_e32 v137, v235
	s_ashr_i32 s39, s38, 31
	v_mov_b64_e32 v[142:143], s[14:15]
	v_lshl_add_u64 v[144:145], s[38:39], 2, v[192:193]
	v_mad_u64_u32 v[142:143], s[74:75], v144, s71, v[142:143]
	v_mad_i32_i24 v143, v145, s71, v143
	v_lshlrev_b32_e32 v188, 2, v194
	v_lshl_add_u64 v[142:143], v[142:143], 0, s[46:47]
	v_lshl_add_u64 v[142:143], v[142:143], 0, v[188:189]
	s_nop 0
	v_pk_mul_f32 v[132:133], v[132:133], v[140:141] op_sel_hi:[1,0]
	v_pk_mul_f32 v[130:131], v[130:131], v[140:141] op_sel_hi:[1,0]
	v_pk_mul_f32 v[132:133], v[72:73], v[132:133]
	v_pk_mul_f32 v[130:131], v[70:71], v[130:131]
	global_store_dwordx4 v[142:143], v[130:133], off
	s_nop 1
	v_mov_b32_e32 v130, s94
	s_nop 0
	v_pk_mul_f32 v[132:133], v[136:137], v[130:131] op_sel_hi:[1,0]
	v_pk_mul_f32 v[130:131], v[134:135], v[130:131] op_sel_hi:[1,0]
	v_pk_mul_f32 v[132:133], v[8:9], v[132:133]
	v_pk_mul_f32 v[130:131], v[6:7], v[130:131]
	global_store_dwordx4 v[142:143], v[130:133], off offset:16
	s_nop 1
	v_mov_b32_e32 v140, s94
	s_nop 0
	s_nop 1
	v_mov_b32_e32 v130, v160
	v_mov_b32_e32 v131, v161
	v_mov_b32_e32 v132, v162
	v_mov_b32_e32 v133, v163
	s_nop 1
	v_mov_b32_e32 v134, v236
	v_mov_b32_e32 v135, v237
	v_mov_b32_e32 v136, v238
	v_mov_b32_e32 v137, v239
	s_nop 0
	v_pk_mul_f32 v[132:133], v[132:133], v[140:141] op_sel_hi:[1,0]
	v_pk_mul_f32 v[130:131], v[130:131], v[140:141] op_sel_hi:[1,0]
	v_pk_mul_f32 v[132:133], v[68:69], v[132:133]
	v_pk_mul_f32 v[130:131], v[66:67], v[130:131]
	global_store_dwordx4 v[142:143], v[130:133], off offset:512
	s_nop 1
	v_mov_b32_e32 v130, s94
	s_nop 0
	v_pk_mul_f32 v[132:133], v[136:137], v[130:131] op_sel_hi:[1,0]
	v_pk_mul_f32 v[130:131], v[134:135], v[130:131] op_sel_hi:[1,0]
	v_pk_mul_f32 v[132:133], v[4:5], v[132:133]
	v_pk_mul_f32 v[130:131], v[2:3], v[130:131]
	global_store_dwordx4 v[142:143], v[130:133], off offset:528
	s_nop 1
	v_mov_b64_e32 v[130:131], s[44:45]
.LBB0_1887:
	s_or_b64 exec, exec, s[42:43]
	v_lshl_or_b32 v212, s40, 7, v194
	v_ashrrev_i32_e32 v213, 31, v212
	v_lshlrev_b64 v[132:133], 2, v[212:213]
	v_lshl_add_u64 v[206:207], s[56:57], 0, v[132:133]
	v_lshl_add_u64 v[208:209], v[130:131], 2, v[196:197]
	v_add_co_u32_e32 v130, vcc, 0x15000, v206
	v_lshl_add_u64 v[210:211], s[58:59], 0, v[132:133]
	s_nop 0
	v_addc_co_u32_e32 v131, vcc, 0, v207, vcc
	v_add_co_u32_e32 v132, vcc, 0x2b000, v206
	s_waitcnt lgkmcnt(0)
	s_barrier
	v_mov_b32_e32 v140, 0
	v_addc_co_u32_e32 v133, vcc, 0, v207, vcc
	v_mov_b32_e32 v134, s94
	v_mov_b32_e32 v136, v224
	v_mov_b32_e32 v137, v225
	v_mov_b32_e32 v138, v226
	v_mov_b32_e32 v139, v227
	s_nop 0
	s_nop 0
	s_nop 0
	v_add_co_u32_e32 v130, vcc, 0xa000, v210
	v_mov_b32_e32 v146, 0
	s_nop 0
	v_addc_co_u32_e32 v131, vcc, 0, v211, vcc
	v_add_co_u32_e32 v142, vcc, 0xa000, v206
	v_mov_b32_e32 v130, v228
	v_mov_b32_e32 v131, v229
	v_mov_b32_e32 v132, v230
	v_mov_b32_e32 v133, v231
	s_nop 0
	s_nop 0
	s_nop 0
	v_addc_co_u32_e32 v143, vcc, 0, v207, vcc
	v_add_co_u32_e32 v144, vcc, 0x20000, v206
	v_mov_b32_e32 v147, 0
	s_nop 0
	v_addc_co_u32_e32 v145, vcc, 0, v207, vcc
	s_nop 0
	s_nop 0
	v_add_co_u32_e32 v142, vcc, 0x35000, v206
	v_mov_b32_e32 v144, 0
	s_nop 0
	v_addc_co_u32_e32 v143, vcc, 0, v207, vcc
	s_nop 0
	v_mov_b32_e32 v145, 0
	s_and_saveexec_b64 s[40:41], s[26:27]
	ds_read_b128 v[144:147], v215
	s_or_b64 exec, exec, s[40:41]
	v_mov_b32_e32 v141, 0
	v_mov_b32_e32 v142, 0
	v_mov_b32_e32 v143, 0
	s_and_saveexec_b64 s[40:41], s[26:27]
	ds_read_b128 v[140:143], v215 offset:512
	s_or_b64 exec, exec, s[40:41]
	s_nop 0
	v_pk_mul_f32 v[176:177], v[176:177], v[134:135] op_sel_hi:[1,0]
	v_pk_mul_f32 v[178:179], v[178:179], v[134:135] op_sel_hi:[1,0]
	v_pk_mul_f32 v[226:227], v[148:149], v[176:177]
	v_pk_mul_f32 v[230:231], v[176:177], v[156:157]
	v_pk_mul_f32 v[176:177], v[176:177], v[152:153]
	v_pk_mul_f32 v[152:153], v[134:135], v[162:163] op_sel_hi:[0,1]
	v_pk_mul_f32 v[134:135], v[134:135], v[160:161] op_sel_hi:[0,1]
	v_pk_mul_f32 v[224:225], v[150:151], v[178:179]
	v_pk_mul_f32 v[228:229], v[178:179], v[158:159]
	v_pk_mul_f32 v[178:179], v[178:179], v[154:155]
	v_pk_mul_f32 v[154:155], v[168:169], v[134:135]
	v_mov_b32_e32 v160, 0
	v_mov_b32_e32 v161, 0
	v_mov_b32_e32 v168, 0
	v_mov_b32_e32 v169, 0
	v_pk_mul_f32 v[156:157], v[134:135], v[164:165]
	v_pk_mul_f32 v[158:159], v[134:135], v[172:173]
	v_mov_b32_e32 v135, 0
	s_waitcnt lgkmcnt(0)
	v_mov_b32_dpp v160, v144 row_ror:1 row_mask:0xf bank_mask:0xf
	v_mov_b32_e32 v172, 0
	v_mov_b32_dpp v161, v144 row_ror:2 row_mask:0xf bank_mask:0xf
	v_mov_b32_dpp v168, v145 row_ror:1 row_mask:0xf bank_mask:0xf
	v_mov_b32_dpp v169, v145 row_ror:2 row_mask:0xf bank_mask:0xf
	v_mov_b32_e32 v238, 0
	v_mov_b32_e32 v144, 0
	v_mov_b32_e32 v239, 0
	v_mov_b32_e32 v145, 0
	v_mov_b32_dpp v135, v126 row_ror:1 row_mask:0xf bank_mask:0xf
	v_mov_b32_dpp v172, v126 row_ror:2 row_mask:0xf bank_mask:0xf
	v_mov_b32_e32 v223, 0
	v_mov_b32_e32 v233, 0
	v_mov_b32_e32 v235, 0
	v_mov_b32_e32 v237, 0
	v_mov_b32_dpp v238, v122 row_ror:1 row_mask:0xf bank_mask:0xf
	v_mov_b32_dpp v144, v140 row_ror:1 row_mask:0xf bank_mask:0xf
	v_mov_b32_dpp v239, v122 row_ror:2 row_mask:0xf bank_mask:0xf
	v_mov_b32_dpp v145, v140 row_ror:2 row_mask:0xf bank_mask:0xf
	v_mov_b32_dpp v223, v146 row_ror:1 row_mask:0xf bank_mask:0xf
	v_mov_b32_dpp v233, v146 row_ror:2 row_mask:0xf bank_mask:0xf
	v_mov_b32_dpp v235, v147 row_ror:1 row_mask:0xf bank_mask:0xf
	v_mov_b32_dpp v237, v147 row_ror:2 row_mask:0xf bank_mask:0xf
	v_cndmask_b32_e64 v163, v238, v144, s[8:9]
	v_cndmask_b32_e64 v162, v135, v160, s[8:9]
	v_cndmask_b32_e64 v165, v239, v145, s[6:7]
	v_cndmask_b32_e64 v164, v172, v161, s[6:7]
	v_mov_b32_e32 v160, v126
	v_mov_b32_e32 v161, v122
	v_mov_b32_e32 v144, v176
	v_mov_b32_e32 v145, v158
	v_mov_b32_e32 v146, v136
	v_mov_b32_e32 v147, v130
	v_mov_b32_e32 v176, 0
	v_mov_b32_e32 v122, 0
	v_pk_mul_f32 v[150:151], v[152:153], v[166:167]
	v_mov_b32_e32 v173, 0
	v_pk_fma_f32 v[166:167], v[160:161], v[144:145], v[146:147]
	v_mov_b32_e32 v160, v230
	v_mov_b32_e32 v161, v156
	v_mov_b32_dpp v176, v123 row_ror:1 row_mask:0xf bank_mask:0xf
	v_mov_b32_dpp v122, v141 row_ror:1 row_mask:0xf bank_mask:0xf
	v_mov_b32_e32 v126, 0
	v_pk_mul_f32 v[148:149], v[170:171], v[152:153]
	v_pk_mul_f32 v[152:153], v[152:153], v[174:175]
	v_mov_b32_dpp v173, v127 row_ror:1 row_mask:0xf bank_mask:0xf
	v_mov_b32_e32 v174, 0
	v_pk_fma_f32 v[166:167], v[160:161], v[162:163], v[166:167]
	v_mov_b32_e32 v162, v226
	v_mov_b32_e32 v226, 0
	v_mov_b32_dpp v126, v141 row_ror:2 row_mask:0xf bank_mask:0xf
	v_cndmask_b32_e64 v141, v176, v122, s[8:9]
	v_mov_b32_e32 v122, v127
	v_mov_b32_e32 v158, v177
	v_mov_b32_e32 v130, v137
	v_mov_b32_dpp v174, v127 row_ror:2 row_mask:0xf bank_mask:0xf
	v_mov_b32_e32 v163, v154
	v_mov_b32_dpp v226, v123 row_ror:2 row_mask:0xf bank_mask:0xf
	v_cndmask_b32_e64 v140, v173, v168, s[8:9]
	v_pk_fma_f32 v[122:123], v[122:123], v[158:159], v[130:131]
	v_mov_b32_e32 v156, v231
	v_mov_b32_e32 v175, 0
	v_pk_fma_f32 v[170:171], v[162:163], v[164:165], v[166:167]
	v_cndmask_b32_e64 v165, v226, v126, s[6:7]
	v_cndmask_b32_e64 v164, v174, v169, s[6:7]
	v_pk_fma_f32 v[122:123], v[156:157], v[140:141], v[122:123]
	v_mov_b32_e32 v154, v227
	v_mov_b32_e32 v177, 0
	v_mov_b32_e32 v126, 0
	v_mov_b32_dpp v175, v128 row_ror:1 row_mask:0xf bank_mask:0xf
	v_mov_b32_e32 v232, 0
	v_pk_fma_f32 v[122:123], v[154:155], v[164:165], v[122:123]
	v_mov_b32_dpp v177, v124 row_ror:1 row_mask:0xf bank_mask:0xf
	v_mov_b32_dpp v126, v142 row_ror:1 row_mask:0xf bank_mask:0xf
	v_mov_b32_e32 v227, 0
	v_mov_b32_e32 v136, 0
	v_mov_b32_e32 v166, v128
	v_mov_b32_e32 v167, v124
	v_mov_b32_e32 v140, v178
	v_mov_b32_e32 v141, v152
	v_mov_b32_e32 v164, v138
	v_mov_b32_e32 v165, v132
	v_mov_b32_dpp v232, v128 row_ror:2 row_mask:0xf bank_mask:0xf
	v_mov_b32_dpp v227, v124 row_ror:2 row_mask:0xf bank_mask:0xf
	v_mov_b32_dpp v136, v142 row_ror:2 row_mask:0xf bank_mask:0xf
	v_cndmask_b32_e64 v127, v177, v126, s[8:9]
	v_cndmask_b32_e64 v126, v175, v223, s[8:9]
	v_pk_fma_f32 v[168:169], v[166:167], v[140:141], v[164:165]
	v_mov_b32_e32 v166, v228
	v_mov_b32_e32 v167, v150
	v_mov_b32_e32 v178, 0
	v_mov_b32_e32 v124, 0
	v_mov_b32_e32 v234, 0
	v_mov_b32_e32 v236, 0
	v_cndmask_b32_e64 v137, v227, v136, s[6:7]
	v_cndmask_b32_e64 v136, v232, v233, s[6:7]
	v_pk_fma_f32 v[126:127], v[166:167], v[126:127], v[168:169]
	v_mov_b32_e32 v168, v224
	v_mov_b32_e32 v169, v148
	v_mov_b32_dpp v178, v125 row_ror:1 row_mask:0xf bank_mask:0xf
	v_mov_b32_dpp v124, v143 row_ror:1 row_mask:0xf bank_mask:0xf
	v_mov_b32_dpp v234, v129 row_ror:1 row_mask:0xf bank_mask:0xf
	v_mov_b32_dpp v236, v129 row_ror:2 row_mask:0xf bank_mask:0xf
	v_pk_fma_f32 v[126:127], v[168:169], v[136:137], v[126:127]
	v_cndmask_b32_e64 v137, v178, v124, s[8:9]
	v_mov_b32_e32 v124, v129
	v_mul_f32_e32 v129, 0xbfb8aa3b, v122
	v_mov_b32_e32 v223, 0
	v_mov_b32_e32 v128, 0
	v_mov_b32_e32 v152, v179
	v_mov_b32_e32 v132, v139
	v_exp_f32_e32 v129, v129
	v_mov_b32_dpp v223, v125 row_ror:2 row_mask:0xf bank_mask:0xf
	v_mov_b32_dpp v128, v143 row_ror:2 row_mask:0xf bank_mask:0xf
	v_cndmask_b32_e64 v136, v234, v235, s[8:9]
	v_pk_fma_f32 v[124:125], v[124:125], v[152:153], v[132:133]
	v_mov_b32_e32 v150, v229
	v_cndmask_b32_e64 v143, v223, v128, s[6:7]
	v_cndmask_b32_e64 v142, v236, v237, s[6:7]
	v_pk_fma_f32 v[124:125], v[150:151], v[136:137], v[124:125]
	v_mov_b32_e32 v148, v225
	v_pk_fma_f32 v[124:125], v[148:149], v[142:143], v[124:125]
	v_add_f32_e32 v129, 1.0, v129
	v_mul_f32_e32 v136, 0xbfb8aa3b, v126
	v_mul_f32_e32 v137, 0xbfb8aa3b, v124
	v_mul_f32_e32 v128, 0xbfb8aa3b, v170
	v_rcp_f32_e32 v129, v129
	v_exp_f32_e32 v136, v136
	v_exp_f32_e32 v137, v137
	v_exp_f32_e32 v128, v128
	v_mul_f32_e32 v122, v122, v129
	v_add_f32_e32 v129, 1.0, v136
	v_add_f32_e32 v136, 1.0, v137
	v_add_f32_e32 v128, 1.0, v128
	v_rcp_f32_e32 v136, v136
	v_rcp_f32_e32 v128, v128
	v_rcp_f32_e32 v129, v129
	v_mul_f32_e32 v122, v122, v123
	v_mul_f32_e32 v124, v124, v136
	v_mul_f32_e32 v128, v170, v128
	v_mul_f32_e32 v123, v126, v129
	v_mul_f32_e32 v124, v124, v125
	v_lshl_add_u32 v188, s38, 8, v1
	v_mul_f32_e32 v128, v128, v171
	v_mul_f32_e32 v123, v123, v127
	v_cvt_pk_bf16_f32 v126, v128, v122
	v_cvt_pk_bf16_f32 v127, v123, v124
	v_mov_b64_e32 v[124:125], s[12:13]
	v_mad_i64_i32 v[122:123], s[38:39], v188, s72, v[124:125]
	v_lshlrev_b64 v[138:139], 1, v[212:213]
	v_mov_b32_e32 v142, 0
	v_mov_b32_e32 v225, 0
	v_lshl_add_u64 v[122:123], v[122:123], 0, v[138:139]
	v_mov_b32_dpp v142, v118 row_ror:1 row_mask:0xf bank_mask:0xf
	v_mov_b32_e32 v143, 0
	v_mov_b32_dpp v225, v114 row_ror:1 row_mask:0xf bank_mask:0xf
	v_mov_b32_e32 v228, 0
	v_mov_b32_e32 v136, v118
	v_mov_b32_e32 v137, v114
	global_store_dwordx2 v[122:123], v[126:127], off
	v_mov_b32_dpp v143, v118 row_ror:2 row_mask:0xf bank_mask:0xf
	v_mov_b32_e32 v170, 0
	v_mov_b32_dpp v228, v114 row_ror:2 row_mask:0xf bank_mask:0xf
	v_cndmask_b32_e64 v127, v225, v238, s[8:9]
	v_cndmask_b32_e64 v126, v142, v135, s[8:9]
	v_pk_fma_f32 v[136:137], v[136:137], v[144:145], v[146:147]
	v_mov_b32_e32 v135, 0
	v_mov_b32_dpp v170, v119 row_ror:1 row_mask:0xf bank_mask:0xf
	v_mov_b32_e32 v171, 0
	v_cndmask_b32_e64 v129, v228, v239, s[6:7]
	v_cndmask_b32_e64 v128, v143, v172, s[6:7]
	v_pk_fma_f32 v[126:127], v[160:161], v[126:127], v[136:137]
	v_mov_b32_dpp v135, v115 row_ror:1 row_mask:0xf bank_mask:0xf
	v_mov_b32_e32 v172, 0
	v_mov_b32_e32 v114, v119
	v_mov_b32_dpp v171, v119 row_ror:2 row_mask:0xf bank_mask:0xf
	v_pk_fma_f32 v[126:127], v[162:163], v[128:129], v[126:127]
	v_mov_b32_dpp v172, v115 row_ror:2 row_mask:0xf bank_mask:0xf
	v_cndmask_b32_e64 v129, v135, v176, s[8:9]
	v_cndmask_b32_e64 v128, v170, v173, s[8:9]
	v_pk_fma_f32 v[114:115], v[114:115], v[158:159], v[130:131]
	v_cndmask_b32_e64 v137, v172, v226, s[6:7]
	v_cndmask_b32_e64 v136, v171, v174, s[6:7]
	v_pk_fma_f32 v[114:115], v[156:157], v[128:129], v[114:115]
	v_mov_b32_e32 v173, 0
	v_mov_b32_e32 v174, 0
	v_mov_b32_e32 v179, 0
	v_mov_b32_e32 v212, 0
	v_pk_fma_f32 v[114:115], v[154:155], v[136:137], v[114:115]
	v_mov_b32_dpp v173, v116 row_ror:1 row_mask:0xf bank_mask:0xf
	v_mov_b32_dpp v174, v116 row_ror:2 row_mask:0xf bank_mask:0xf
	v_mov_b32_e32 v137, v116
	v_mul_f32_e32 v116, 0xbfb8aa3b, v126
	v_mov_b32_dpp v179, v120 row_ror:1 row_mask:0xf bank_mask:0xf
	v_mov_b32_dpp v212, v120 row_ror:2 row_mask:0xf bank_mask:0xf
	v_mov_b32_e32 v136, v120
	v_exp_f32_e32 v120, v116
	v_mov_b32_e32 v213, 0
	v_mov_b32_e32 v224, 0
	v_cndmask_b32_e64 v119, v173, v177, s[8:9]
	v_add_f32_e32 v120, 1.0, v120
	v_mov_b32_dpp v213, v121 row_ror:1 row_mask:0xf bank_mask:0xf
	v_mov_b32_dpp v224, v121 row_ror:2 row_mask:0xf bank_mask:0xf
	v_cndmask_b32_e64 v118, v179, v175, s[8:9]
	v_pk_fma_f32 v[136:137], v[136:137], v[140:141], v[164:165]
	v_mov_b32_e32 v175, 0
	v_mov_b32_e32 v116, v121
	v_rcp_f32_e32 v120, v120
	v_mul_f32_e32 v121, 0xbfb8aa3b, v114
	v_cndmask_b32_e64 v129, v174, v227, s[6:7]
	v_cndmask_b32_e64 v128, v212, v232, s[6:7]
	v_pk_fma_f32 v[118:119], v[166:167], v[118:119], v[136:137]
	v_mov_b32_dpp v175, v117 row_ror:1 row_mask:0xf bank_mask:0xf
	v_mov_b32_e32 v176, 0
	v_exp_f32_e32 v121, v121
	v_pk_fma_f32 v[118:119], v[168:169], v[128:129], v[118:119]
	v_mov_b32_dpp v176, v117 row_ror:2 row_mask:0xf bank_mask:0xf
	v_cndmask_b32_e64 v129, v175, v178, s[8:9]
	v_cndmask_b32_e64 v128, v213, v234, s[8:9]
	v_pk_fma_f32 v[116:117], v[116:117], v[152:153], v[132:133]
	v_cndmask_b32_e64 v137, v176, v223, s[6:7]
	v_cndmask_b32_e64 v136, v224, v236, s[6:7]
	v_pk_fma_f32 v[116:117], v[150:151], v[128:129], v[116:117]
	v_mul_f32_e32 v120, v126, v120
	v_pk_fma_f32 v[116:117], v[148:149], v[136:137], v[116:117]
	v_mul_f32_e32 v120, v120, v127
	v_add_f32_e32 v121, 1.0, v121
	v_mul_f32_e32 v126, 0xbfb8aa3b, v118
	v_mul_f32_e32 v127, 0xbfb8aa3b, v116
	v_rcp_f32_e32 v121, v121
	v_exp_f32_e32 v126, v126
	v_exp_f32_e32 v127, v127
	v_mov_b32_e32 v223, 0
	v_mul_f32_e32 v114, v114, v121
	v_add_f32_e32 v121, 1.0, v126
	v_add_f32_e32 v126, 1.0, v127
	v_rcp_f32_e32 v121, v121
	v_rcp_f32_e32 v126, v126
	v_mul_f32_e32 v114, v114, v115
	v_cvt_pk_bf16_f32 v114, v120, v114
	v_mul_f32_e32 v115, v118, v121
	v_mul_f32_e32 v116, v116, v126
	v_mul_f32_e32 v115, v115, v119
	v_mul_f32_e32 v116, v116, v117
	v_or_b32_e32 v117, 16, v188
	v_cvt_pk_bf16_f32 v115, v115, v116
	v_mad_i64_i32 v[116:117], s[38:39], v117, s72, v[124:125]
	v_mov_b32_e32 v126, 0
	v_lshl_add_u64 v[118:119], v[116:117], 0, v[138:139]
	v_mov_b32_e32 v127, 0
	v_mov_b32_dpp v126, v110 row_ror:1 row_mask:0xf bank_mask:0xf
	v_mov_b32_dpp v223, v106 row_ror:1 row_mask:0xf bank_mask:0xf
	v_mov_b32_e32 v226, 0
	v_mov_b32_e32 v120, v110
	v_mov_b32_e32 v121, v106
	global_store_dwordx2 v[118:119], v[114:115], off
	v_mov_b32_dpp v127, v110 row_ror:2 row_mask:0xf bank_mask:0xf
	v_mov_b32_e32 v128, 0
	v_mov_b32_dpp v226, v106 row_ror:2 row_mask:0xf bank_mask:0xf
	v_cndmask_b32_e64 v115, v223, v225, s[8:9]
	v_cndmask_b32_e64 v114, v126, v142, s[8:9]
	v_pk_fma_f32 v[120:121], v[120:121], v[144:145], v[146:147]
	v_mov_b32_e32 v142, 0
	v_mov_b32_dpp v128, v111 row_ror:1 row_mask:0xf bank_mask:0xf
	v_mov_b32_e32 v129, 0
	v_cndmask_b32_e64 v117, v226, v228, s[6:7]
	v_cndmask_b32_e64 v116, v127, v143, s[6:7]
	v_pk_fma_f32 v[114:115], v[160:161], v[114:115], v[120:121]
	v_mov_b32_dpp v142, v107 row_ror:1 row_mask:0xf bank_mask:0xf
	v_mov_b32_e32 v143, 0
	v_mov_b32_e32 v106, v111
	v_mov_b32_dpp v129, v111 row_ror:2 row_mask:0xf bank_mask:0xf
	v_pk_fma_f32 v[114:115], v[162:163], v[116:117], v[114:115]
	v_mov_b32_dpp v143, v107 row_ror:2 row_mask:0xf bank_mask:0xf
	v_cndmask_b32_e64 v117, v142, v135, s[8:9]
	v_cndmask_b32_e64 v116, v128, v170, s[8:9]
	v_pk_fma_f32 v[106:107], v[106:107], v[158:159], v[130:131]
	v_cndmask_b32_e64 v121, v143, v172, s[6:7]
	v_cndmask_b32_e64 v120, v129, v171, s[6:7]
	v_pk_fma_f32 v[106:107], v[156:157], v[116:117], v[106:107]
	v_mov_b32_e32 v135, 0
	v_mov_b32_e32 v170, 0
	v_pk_fma_f32 v[106:107], v[154:155], v[120:121], v[106:107]
	v_mov_b32_dpp v135, v108 row_ror:1 row_mask:0xf bank_mask:0xf
	v_mov_b32_dpp v170, v108 row_ror:2 row_mask:0xf bank_mask:0xf
	v_mov_b32_e32 v121, v108
	v_mul_f32_e32 v108, 0xbfb8aa3b, v114
	v_mov_b32_e32 v136, 0
	v_exp_f32_e32 v172, v108
	v_mov_b32_e32 v137, 0
	v_mov_b32_dpp v136, v112 row_ror:1 row_mask:0xf bank_mask:0xf
	v_mov_b32_e32 v120, v112
	v_mov_b32_dpp v137, v112 row_ror:2 row_mask:0xf bank_mask:0xf
	v_mov_b32_e32 v177, 0
	v_cndmask_b32_e64 v111, v135, v173, s[8:9]
	v_cndmask_b32_e64 v110, v136, v179, s[8:9]
	v_pk_fma_f32 v[120:121], v[120:121], v[140:141], v[164:165]
	v_mov_b32_e32 v112, 0
	v_mov_b32_dpp v177, v113 row_ror:1 row_mask:0xf bank_mask:0xf
	v_mov_b32_e32 v178, 0
	v_cndmask_b32_e64 v117, v170, v174, s[6:7]
	v_cndmask_b32_e64 v116, v137, v212, s[6:7]
	v_pk_fma_f32 v[110:111], v[166:167], v[110:111], v[120:121]
	v_mov_b32_dpp v112, v109 row_ror:1 row_mask:0xf bank_mask:0xf
	v_mov_b32_e32 v171, 0
	v_mov_b32_e32 v108, v113
	v_mov_b32_dpp v178, v113 row_ror:2 row_mask:0xf bank_mask:0xf
	v_pk_fma_f32 v[110:111], v[168:169], v[116:117], v[110:111]
	v_mov_b32_dpp v171, v109 row_ror:2 row_mask:0xf bank_mask:0xf
	v_cndmask_b32_e64 v117, v112, v175, s[8:9]
	v_cndmask_b32_e64 v116, v177, v213, s[8:9]
	v_pk_fma_f32 v[108:109], v[108:109], v[152:153], v[132:133]
	v_add_f32_e32 v113, 1.0, v172
	v_pk_fma_f32 v[108:109], v[150:151], v[116:117], v[108:109]
	v_rcp_f32_e32 v113, v113
	v_mul_f32_e32 v116, 0xbfb8aa3b, v106
	v_exp_f32_e32 v116, v116
	v_cndmask_b32_e64 v121, v171, v176, s[6:7]
	v_cndmask_b32_e64 v120, v178, v224, s[6:7]
	v_pk_fma_f32 v[108:109], v[148:149], v[120:121], v[108:109]
	v_mul_f32_e32 v113, v114, v113
	v_mul_f32_e32 v113, v113, v115
	v_add_f32_e32 v114, 1.0, v116
	v_mul_f32_e32 v115, 0xbfb8aa3b, v110
	v_mul_f32_e32 v116, 0xbfb8aa3b, v108
	v_rcp_f32_e32 v114, v114
	v_exp_f32_e32 v115, v115
	v_exp_f32_e32 v116, v116
	v_mov_b32_e32 v117, 0
	v_mul_f32_e32 v106, v106, v114
	v_add_f32_e32 v114, 1.0, v115
	v_add_f32_e32 v115, 1.0, v116
	v_rcp_f32_e32 v114, v114
	v_rcp_f32_e32 v115, v115
	v_mul_f32_e32 v106, v106, v107
	v_cvt_pk_bf16_f32 v106, v113, v106
	v_mul_f32_e32 v107, v110, v114
	v_mul_f32_e32 v108, v108, v115
	v_mul_f32_e32 v107, v107, v111
	v_mul_f32_e32 v108, v108, v109
	v_or_b32_e32 v109, 32, v188
	v_cvt_pk_bf16_f32 v107, v107, v108
	v_mad_i64_i32 v[108:109], s[38:39], v109, s72, v[124:125]
	v_lshl_add_u64 v[120:121], v[108:109], 0, v[138:139]
	global_store_dwordx2 v[120:121], v[106:107], off
	v_mov_b32_e32 v106, 0
	v_mov_b32_e32 v107, 0
	v_mov_b32_e32 v108, 0
	v_mov_b32_dpp v106, v102 row_ror:1 row_mask:0xf bank_mask:0xf
	v_mov_b32_dpp v107, v98 row_ror:1 row_mask:0xf bank_mask:0xf
	v_mov_b32_e32 v109, 0
	v_mov_b32_e32 v110, v102
	v_mov_b32_e32 v111, v98
	v_mov_b32_dpp v108, v102 row_ror:2 row_mask:0xf bank_mask:0xf
	v_mov_b32_dpp v109, v98 row_ror:2 row_mask:0xf bank_mask:0xf
	v_cndmask_b32_e64 v107, v107, v223, s[8:9]
	v_cndmask_b32_e64 v106, v106, v126, s[8:9]
	v_pk_fma_f32 v[110:111], v[110:111], v[144:145], v[146:147]
	v_mov_b32_e32 v98, 0
	v_mov_b32_e32 v113, 0
	v_cndmask_b32_e64 v109, v109, v226, s[6:7]
	v_cndmask_b32_e64 v108, v108, v127, s[6:7]
	v_pk_fma_f32 v[106:107], v[160:161], v[106:107], v[110:111]
	v_mov_b32_dpp v98, v99 row_ror:1 row_mask:0xf bank_mask:0xf
	v_mov_b32_dpp v113, v103 row_ror:1 row_mask:0xf bank_mask:0xf
	v_mov_b32_e32 v114, 0
	v_pk_fma_f32 v[106:107], v[162:163], v[108:109], v[106:107]
	v_mov_b32_e32 v102, 0
	v_cndmask_b32_e64 v109, v98, v142, s[8:9]
	v_mov_b32_e32 v98, v103
	v_mov_b32_dpp v114, v103 row_ror:2 row_mask:0xf bank_mask:0xf
	v_mov_b32_dpp v102, v99 row_ror:2 row_mask:0xf bank_mask:0xf
	v_cndmask_b32_e64 v108, v113, v128, s[8:9]
	v_pk_fma_f32 v[98:99], v[98:99], v[158:159], v[130:131]
	v_mov_b32_e32 v115, 0
	v_cndmask_b32_e64 v111, v102, v143, s[6:7]
	v_cndmask_b32_e64 v110, v114, v129, s[6:7]
	v_pk_fma_f32 v[98:99], v[156:157], v[108:109], v[98:99]
	v_mov_b32_e32 v102, 0
	v_mov_b32_dpp v115, v104 row_ror:1 row_mask:0xf bank_mask:0xf
	v_mov_b32_e32 v116, 0
	v_pk_fma_f32 v[98:99], v[154:155], v[110:111], v[98:99]
	v_mov_b32_dpp v102, v100 row_ror:1 row_mask:0xf bank_mask:0xf
	v_mov_b32_e32 v108, 0
	v_mov_b32_e32 v110, v104
	v_mov_b32_e32 v111, v100
	v_mov_b32_dpp v116, v104 row_ror:2 row_mask:0xf bank_mask:0xf
	v_mov_b32_dpp v108, v100 row_ror:2 row_mask:0xf bank_mask:0xf
	v_cndmask_b32_e64 v103, v102, v135, s[8:9]
	v_cndmask_b32_e64 v102, v115, v136, s[8:9]
	v_pk_fma_f32 v[110:111], v[110:111], v[140:141], v[164:165]
	v_mov_b32_e32 v100, 0
	v_cndmask_b32_e64 v109, v108, v170, s[6:7]
	v_cndmask_b32_e64 v108, v116, v137, s[6:7]
	v_pk_fma_f32 v[102:103], v[166:167], v[102:103], v[110:111]
	v_mov_b32_dpp v100, v101 row_ror:1 row_mask:0xf bank_mask:0xf
	v_mov_b32_e32 v104, 0
	v_pk_fma_f32 v[102:103], v[168:169], v[108:109], v[102:103]
	v_cndmask_b32_e64 v109, v100, v112, s[8:9]
	v_mov_b32_dpp v104, v101 row_ror:2 row_mask:0xf bank_mask:0xf
	v_mul_f32_e32 v100, 0xbfb8aa3b, v106
	v_cndmask_b32_e64 v111, v104, v171, s[6:7]
	v_exp_f32_e32 v104, v100
	v_mov_b32_e32 v172, 0
	v_mov_b32_dpp v117, v105 row_ror:1 row_mask:0xf bank_mask:0xf
	v_mov_b32_e32 v100, v105
	v_add_f32_e32 v104, 1.0, v104
	v_mov_b32_dpp v172, v105 row_ror:2 row_mask:0xf bank_mask:0xf
	v_rcp_f32_e32 v104, v104
	v_mul_f32_e32 v105, 0xbfb8aa3b, v98
	v_exp_f32_e32 v105, v105
	v_cndmask_b32_e64 v108, v117, v177, s[8:9]
	v_pk_fma_f32 v[100:101], v[100:101], v[152:153], v[132:133]
	v_cndmask_b32_e64 v110, v172, v178, s[6:7]
	v_pk_fma_f32 v[100:101], v[150:151], v[108:109], v[100:101]
	v_mul_f32_e32 v104, v106, v104
	v_pk_fma_f32 v[100:101], v[148:149], v[110:111], v[100:101]
	v_mul_f32_e32 v104, v104, v107
	v_add_f32_e32 v105, 1.0, v105
	v_mul_f32_e32 v106, 0xbfb8aa3b, v102
	v_mul_f32_e32 v107, 0xbfb8aa3b, v100
	v_rcp_f32_e32 v105, v105
	v_exp_f32_e32 v106, v106
	v_exp_f32_e32 v107, v107
	v_mov_b32_e32 v134, 0
	v_mul_f32_e32 v98, v98, v105
	v_add_f32_e32 v105, 1.0, v106
	v_add_f32_e32 v106, 1.0, v107
	v_rcp_f32_e32 v105, v105
	v_rcp_f32_e32 v106, v106
	v_mul_f32_e32 v98, v98, v99
	v_cvt_pk_bf16_f32 v98, v104, v98
	v_mul_f32_e32 v99, v102, v105
	v_mul_f32_e32 v100, v100, v106
	v_mul_f32_e32 v99, v99, v103
	v_mul_f32_e32 v100, v100, v101
	v_or_b32_e32 v101, 48, v188
	v_cvt_pk_bf16_f32 v99, v99, v100
	v_mad_i64_i32 v[100:101], s[38:39], v101, s72, v[124:125]
	v_lshl_add_u64 v[124:125], v[100:101], 0, v[138:139]
	global_store_dwordx2 v[124:125], v[98:99], off
	v_mov_b32_e32 v100, 0
	v_mov_b32_e32 v101, 0
	v_mov_b32_e32 v102, 0
	v_mov_b32_e32 v103, 0
	s_and_saveexec_b64 s[38:39], s[4:5]
	ds_read_b128 v[100:103], v216
	s_or_b64 exec, exec, s[38:39]
	v_mov_b32_e32 v135, 0
	v_mov_b32_e32 v136, 0
	v_mov_b32_e32 v137, 0
	s_and_saveexec_b64 s[38:39], s[4:5]
	ds_read_b128 v[134:137], v216 offset:512
	s_or_b64 exec, exec, s[38:39]
	v_mov_b32_e32 v116, 0
	v_mov_b32_e32 v126, 0
	v_mov_b32_e32 v108, 0
	v_mov_b32_e32 v106, 0
	s_waitcnt lgkmcnt(0)
	v_mov_b32_dpp v116, v102 row_ror:1 row_mask:0xf bank_mask:0xf
	v_mov_b32_dpp v126, v102 row_ror:2 row_mask:0xf bank_mask:0xf
	v_mov_b32_e32 v143, 0
	v_mov_b32_e32 v102, 0
	v_mov_b32_e32 v170, 0
	v_mov_b32_dpp v108, v94 row_ror:1 row_mask:0xf bank_mask:0xf
	v_mov_b32_dpp v106, v100 row_ror:1 row_mask:0xf bank_mask:0xf
	v_mov_b32_e32 v109, 0
	v_mov_b32_e32 v110, 0
	v_mov_b32_e32 v104, v94
	v_mov_b32_e32 v105, v90
	v_mov_b32_e32 v128, 0
	v_mov_b32_e32 v142, 0
	v_mov_b32_dpp v143, v90 row_ror:1 row_mask:0xf bank_mask:0xf
	v_mov_b32_dpp v102, v134 row_ror:1 row_mask:0xf bank_mask:0xf
	v_mov_b32_dpp v170, v90 row_ror:2 row_mask:0xf bank_mask:0xf
	v_mov_b32_e32 v90, 0
	v_mov_b32_dpp v109, v94 row_ror:2 row_mask:0xf bank_mask:0xf
	v_mov_b32_dpp v110, v100 row_ror:2 row_mask:0xf bank_mask:0xf
	v_mov_b32_dpp v128, v103 row_ror:1 row_mask:0xf bank_mask:0xf
	v_mov_b32_dpp v142, v103 row_ror:2 row_mask:0xf bank_mask:0xf
	v_mov_b32_dpp v90, v134 row_ror:2 row_mask:0xf bank_mask:0xf
	v_cndmask_b32_e64 v103, v143, v102, s[8:9]
	v_cndmask_b32_e64 v102, v108, v106, s[8:9]
	v_pk_fma_f32 v[104:105], v[104:105], v[144:145], v[146:147]
	v_cndmask_b32_e64 v107, v170, v90, s[6:7]
	v_cndmask_b32_e64 v106, v109, v110, s[6:7]
	v_pk_fma_f32 v[102:103], v[160:161], v[102:103], v[104:105]
	v_mov_b32_e32 v111, 0
	v_mov_b32_e32 v112, 0
	v_mov_b32_e32 v113, 0
	v_pk_fma_f32 v[102:103], v[162:163], v[106:107], v[102:103]
	v_mov_b32_e32 v106, 0
	v_mov_b32_e32 v90, 0
	v_mov_b32_dpp v111, v95 row_ror:1 row_mask:0xf bank_mask:0xf
	v_mov_b32_dpp v112, v101 row_ror:1 row_mask:0xf bank_mask:0xf
	v_mov_b32_dpp v113, v95 row_ror:2 row_mask:0xf bank_mask:0xf
	v_mov_b32_e32 v94, v95
	v_mov_b32_e32 v95, v91
	v_mov_b32_dpp v106, v91 row_ror:1 row_mask:0xf bank_mask:0xf
	v_mov_b32_dpp v90, v135 row_ror:1 row_mask:0xf bank_mask:0xf
	v_mov_b32_e32 v107, 0
	v_pk_fma_f32 v[94:95], v[94:95], v[158:159], v[130:131]
	v_mov_b32_e32 v114, 0
	v_mov_b32_dpp v107, v91 row_ror:2 row_mask:0xf bank_mask:0xf
	v_cndmask_b32_e64 v91, v106, v90, s[8:9]
	v_cndmask_b32_e64 v90, v111, v112, s[8:9]
	v_mov_b32_e32 v115, 0
	v_mov_b32_e32 v104, 0
	v_pk_fma_f32 v[90:91], v[156:157], v[90:91], v[94:95]
	v_mov_b32_e32 v110, 0
	v_mov_b32_e32 v94, 0
	v_mov_b32_e32 v112, 0
	v_mov_b32_dpp v114, v101 row_ror:2 row_mask:0xf bank_mask:0xf
	v_mov_b32_dpp v115, v96 row_ror:1 row_mask:0xf bank_mask:0xf
	v_mov_b32_e32 v117, 0
	v_mov_b32_e32 v100, v96
	v_mov_b32_e32 v101, v92
	v_mov_b32_dpp v104, v135 row_ror:2 row_mask:0xf bank_mask:0xf
	v_mov_b32_dpp v110, v92 row_ror:1 row_mask:0xf bank_mask:0xf
	v_mov_b32_dpp v94, v136 row_ror:1 row_mask:0xf bank_mask:0xf
	v_mov_b32_dpp v112, v92 row_ror:2 row_mask:0xf bank_mask:0xf
	v_mov_b32_e32 v92, 0
	v_mov_b32_dpp v117, v96 row_ror:2 row_mask:0xf bank_mask:0xf
	v_cndmask_b32_e64 v105, v107, v104, s[6:7]
	v_cndmask_b32_e64 v104, v113, v114, s[6:7]
	v_mov_b32_dpp v92, v136 row_ror:2 row_mask:0xf bank_mask:0xf
	v_cndmask_b32_e64 v95, v110, v94, s[8:9]
	v_cndmask_b32_e64 v94, v115, v116, s[8:9]
	v_pk_fma_f32 v[100:101], v[100:101], v[140:141], v[164:165]
	v_pk_fma_f32 v[90:91], v[154:155], v[104:105], v[90:91]
	v_cndmask_b32_e64 v105, v112, v92, s[6:7]
	v_cndmask_b32_e64 v104, v117, v126, s[6:7]
	v_pk_fma_f32 v[94:95], v[166:167], v[94:95], v[100:101]
	v_mov_b32_e32 v127, 0
	v_mov_b32_e32 v129, 0
	v_pk_fma_f32 v[94:95], v[168:169], v[104:105], v[94:95]
	v_mov_b32_e32 v104, 0
	v_mov_b32_e32 v92, 0
	v_mov_b32_dpp v127, v97 row_ror:1 row_mask:0xf bank_mask:0xf
	v_mov_b32_dpp v129, v97 row_ror:2 row_mask:0xf bank_mask:0xf
	v_mov_b32_e32 v96, v97
	v_mov_b32_e32 v97, v93
	v_mov_b32_dpp v104, v93 row_ror:1 row_mask:0xf bank_mask:0xf
	v_mov_b32_dpp v92, v137 row_ror:1 row_mask:0xf bank_mask:0xf
	v_mov_b32_e32 v105, 0
	v_pk_fma_f32 v[96:97], v[96:97], v[152:153], v[132:133]
	v_mov_b32_e32 v100, 0
	v_mov_b32_dpp v105, v93 row_ror:2 row_mask:0xf bank_mask:0xf
	v_cndmask_b32_e64 v93, v104, v92, s[8:9]
	v_cndmask_b32_e64 v92, v127, v128, s[8:9]
	v_pk_fma_f32 v[92:93], v[150:151], v[92:93], v[96:97]
	v_mul_f32_e32 v97, 0xbfb8aa3b, v90
	v_mov_b32_dpp v100, v137 row_ror:2 row_mask:0xf bank_mask:0xf
	v_exp_f32_e32 v97, v97
	v_cndmask_b32_e64 v101, v105, v100, s[6:7]
	v_mul_f32_e32 v100, 0xbfb8aa3b, v102
	v_exp_f32_e32 v114, v100
	v_cndmask_b32_e64 v100, v129, v142, s[6:7]
	v_pk_fma_f32 v[92:93], v[148:149], v[100:101], v[92:93]
	v_add_f32_e32 v97, 1.0, v97
	v_mul_f32_e32 v100, 0xbfb8aa3b, v94
	v_mul_f32_e32 v101, 0xbfb8aa3b, v92
	v_rcp_f32_e32 v97, v97
	v_exp_f32_e32 v100, v100
	v_exp_f32_e32 v101, v101
	v_add_f32_e32 v96, 1.0, v114
	v_mul_f32_e32 v90, v90, v97
	v_add_f32_e32 v97, 1.0, v100
	v_add_f32_e32 v100, 1.0, v101
	v_rcp_f32_e32 v97, v97
	v_rcp_f32_e32 v100, v100
	v_rcp_f32_e32 v96, v96
	v_mul_f32_e32 v90, v90, v91
	v_mul_f32_e32 v91, v94, v97
	v_mul_f32_e32 v92, v92, v100
	v_mul_f32_e32 v96, v102, v96
	v_mul_f32_e32 v91, v91, v95
	v_mul_f32_e32 v93, v92, v93
	v_add_u32_e32 v99, 0x80, v188
	v_mul_f32_e32 v96, v96, v103
	v_cvt_pk_bf16_f32 v92, v96, v90
	v_cvt_pk_bf16_f32 v93, v91, v93
	v_mov_b64_e32 v[90:91], s[12:13]
	v_mad_i64_i32 v[94:95], s[38:39], v99, s72, v[90:91]
	v_lshl_add_u64 v[96:97], v[94:95], 0, v[138:139]
	v_mov_b32_e32 v99, 0
	v_mov_b32_e32 v142, 0
	global_store_dwordx2 v[96:97], v[92:93], off
	v_mov_b32_dpp v99, v86 row_ror:1 row_mask:0xf bank_mask:0xf
	v_mov_b32_e32 v114, 0
	v_mov_b32_e32 v92, v86
	v_mov_b32_e32 v93, v82
	v_mov_b32_dpp v142, v82 row_ror:1 row_mask:0xf bank_mask:0xf
	v_mov_b32_e32 v171, 0
	v_mov_b32_dpp v114, v86 row_ror:2 row_mask:0xf bank_mask:0xf
	v_cndmask_b32_e64 v101, v142, v143, s[8:9]
	v_mov_b32_dpp v171, v82 row_ror:2 row_mask:0xf bank_mask:0xf
	v_cndmask_b32_e64 v100, v99, v108, s[8:9]
	v_pk_fma_f32 v[92:93], v[92:93], v[144:145], v[146:147]
	v_cndmask_b32_e64 v103, v171, v170, s[6:7]
	v_cndmask_b32_e64 v102, v114, v109, s[6:7]
	v_pk_fma_f32 v[92:93], v[160:161], v[100:101], v[92:93]
	v_mov_b32_e32 v116, 0
	v_pk_fma_f32 v[92:93], v[162:163], v[102:103], v[92:93]
	v_mov_b32_e32 v102, 0
	v_mov_b32_e32 v128, 0
	v_mov_b32_e32 v103, 0
	v_mov_b32_dpp v102, v83 row_ror:1 row_mask:0xf bank_mask:0xf
	v_mov_b32_dpp v116, v87 row_ror:1 row_mask:0xf bank_mask:0xf
	v_mov_b32_dpp v128, v87 row_ror:2 row_mask:0xf bank_mask:0xf
	v_mov_b32_e32 v86, v87
	v_mov_b32_e32 v87, v83
	v_mov_b32_e32 v134, 0
	v_mov_b32_dpp v103, v83 row_ror:2 row_mask:0xf bank_mask:0xf
	v_cndmask_b32_e64 v83, v102, v106, s[8:9]
	v_mov_b32_e32 v106, 0
	v_mov_b32_dpp v134, v88 row_ror:1 row_mask:0xf bank_mask:0xf
	v_mov_b32_e32 v135, 0
	v_mov_b32_e32 v94, v88
	v_mov_b32_e32 v95, v84
	v_cndmask_b32_e64 v82, v116, v111, s[8:9]
	v_cndmask_b32_e64 v101, v103, v107, s[6:7]
	v_pk_fma_f32 v[86:87], v[86:87], v[158:159], v[130:131]
	v_mov_b32_dpp v106, v84 row_ror:1 row_mask:0xf bank_mask:0xf
	v_mov_b32_e32 v107, 0
	v_mov_b32_dpp v135, v88 row_ror:2 row_mask:0xf bank_mask:0xf
	v_cndmask_b32_e64 v100, v128, v113, s[6:7]
	v_pk_fma_f32 v[82:83], v[156:157], v[82:83], v[86:87]
	v_mov_b32_dpp v107, v84 row_ror:2 row_mask:0xf bank_mask:0xf
	v_cndmask_b32_e64 v87, v106, v110, s[8:9]
	v_cndmask_b32_e64 v86, v134, v115, s[8:9]
	v_pk_fma_f32 v[94:95], v[94:95], v[140:141], v[164:165]
	v_pk_fma_f32 v[82:83], v[154:155], v[100:101], v[82:83]
	v_cndmask_b32_e64 v101, v107, v112, s[6:7]
	v_cndmask_b32_e64 v100, v135, v117, s[6:7]
	v_pk_fma_f32 v[86:87], v[166:167], v[86:87], v[94:95]
	v_mov_b32_e32 v136, 0
	v_pk_fma_f32 v[86:87], v[168:169], v[100:101], v[86:87]
	v_mov_b32_e32 v100, 0
	v_mov_b32_e32 v137, 0
	v_mov_b32_e32 v101, 0
	v_mov_b32_dpp v100, v85 row_ror:1 row_mask:0xf bank_mask:0xf
	v_mul_f32_e32 v94, 0xbfb8aa3b, v92
	v_mov_b32_dpp v136, v89 row_ror:1 row_mask:0xf bank_mask:0xf
	v_mov_b32_dpp v137, v89 row_ror:2 row_mask:0xf bank_mask:0xf
	v_mov_b32_e32 v88, v89
	v_mov_b32_e32 v89, v85
	v_mov_b32_dpp v101, v85 row_ror:2 row_mask:0xf bank_mask:0xf
	v_cndmask_b32_e64 v85, v100, v104, s[8:9]
	v_exp_f32_e32 v104, v94
	v_cndmask_b32_e64 v84, v136, v127, s[8:9]
	v_pk_fma_f32 v[88:89], v[88:89], v[152:153], v[132:133]
	v_cndmask_b32_e64 v95, v101, v105, s[6:7]
	v_pk_fma_f32 v[84:85], v[150:151], v[84:85], v[88:89]
	v_add_f32_e32 v88, 1.0, v104
	v_rcp_f32_e32 v88, v88
	v_mul_f32_e32 v89, 0xbfb8aa3b, v82
	v_exp_f32_e32 v89, v89
	v_cndmask_b32_e64 v94, v137, v129, s[6:7]
	v_pk_fma_f32 v[84:85], v[148:149], v[94:95], v[84:85]
	v_mul_f32_e32 v88, v92, v88
	v_mul_f32_e32 v88, v88, v93
	v_add_f32_e32 v89, 1.0, v89
	v_mul_f32_e32 v92, 0xbfb8aa3b, v86
	v_mul_f32_e32 v93, 0xbfb8aa3b, v84
	v_rcp_f32_e32 v89, v89
	v_exp_f32_e32 v92, v92
	v_exp_f32_e32 v93, v93
	v_mov_b32_e32 v110, 0
	v_mul_f32_e32 v82, v82, v89
	v_add_f32_e32 v89, 1.0, v92
	v_add_f32_e32 v92, 1.0, v93
	v_rcp_f32_e32 v89, v89
	v_rcp_f32_e32 v92, v92
	v_mul_f32_e32 v82, v82, v83
	v_cvt_pk_bf16_f32 v82, v88, v82
	v_mul_f32_e32 v83, v86, v89
	v_mul_f32_e32 v84, v84, v92
	v_mul_f32_e32 v83, v83, v87
	v_mul_f32_e32 v84, v84, v85
	v_add_u32_e32 v85, 0x90, v188
	v_cvt_pk_bf16_f32 v83, v83, v84
	v_mad_i64_i32 v[84:85], s[38:39], v85, s72, v[90:91]
	v_lshl_add_u64 v[126:127], v[84:85], 0, v[138:139]
	v_mov_b32_e32 v92, 0
	global_store_dwordx2 v[126:127], v[82:83], off
	v_mov_b32_e32 v93, 0
	v_mov_b32_dpp v92, v78 row_ror:1 row_mask:0xf bank_mask:0xf
	v_mov_b32_e32 v82, v78
	v_mov_b32_e32 v83, v74
	v_mov_b32_dpp v110, v74 row_ror:1 row_mask:0xf bank_mask:0xf
	v_mov_b32_e32 v111, 0
	v_mov_b32_dpp v93, v78 row_ror:2 row_mask:0xf bank_mask:0xf
	v_cndmask_b32_e64 v87, v110, v142, s[8:9]
	v_mov_b32_dpp v111, v74 row_ror:2 row_mask:0xf bank_mask:0xf
	v_cndmask_b32_e64 v86, v92, v99, s[8:9]
	v_pk_fma_f32 v[82:83], v[82:83], v[144:145], v[146:147]
	v_cndmask_b32_e64 v89, v111, v171, s[6:7]
	v_cndmask_b32_e64 v88, v93, v114, s[6:7]
	v_pk_fma_f32 v[82:83], v[160:161], v[86:87], v[82:83]
	v_mov_b32_e32 v94, 0
	v_mov_b32_e32 v95, 0
	v_pk_fma_f32 v[82:83], v[162:163], v[88:89], v[82:83]
	v_mov_b32_e32 v88, 0
	v_mov_b32_dpp v94, v79 row_ror:1 row_mask:0xf bank_mask:0xf
	v_mov_b32_dpp v95, v79 row_ror:2 row_mask:0xf bank_mask:0xf
	v_mov_b32_e32 v78, v79
	v_mov_b32_e32 v79, v75
	v_mov_b32_e32 v104, 0
	v_mov_b32_dpp v88, v75 row_ror:1 row_mask:0xf bank_mask:0xf
	v_mov_b32_e32 v89, 0
	v_mov_b32_e32 v99, 0
	v_mov_b32_dpp v104, v80 row_ror:1 row_mask:0xf bank_mask:0xf
	v_mov_b32_e32 v105, 0
	v_mov_b32_e32 v84, v80
	v_mov_b32_e32 v85, v76
	v_mov_b32_dpp v89, v75 row_ror:2 row_mask:0xf bank_mask:0xf
	v_cndmask_b32_e64 v75, v88, v102, s[8:9]
	v_cndmask_b32_e64 v74, v94, v116, s[8:9]
	v_pk_fma_f32 v[78:79], v[78:79], v[158:159], v[130:131]
	v_mov_b32_dpp v99, v76 row_ror:1 row_mask:0xf bank_mask:0xf
	v_mov_b32_e32 v102, 0
	v_mov_b32_dpp v105, v80 row_ror:2 row_mask:0xf bank_mask:0xf
	v_cndmask_b32_e64 v87, v89, v103, s[6:7]
	v_cndmask_b32_e64 v86, v95, v128, s[6:7]
	v_pk_fma_f32 v[74:75], v[156:157], v[74:75], v[78:79]
	v_mov_b32_dpp v102, v76 row_ror:2 row_mask:0xf bank_mask:0xf
	v_cndmask_b32_e64 v79, v99, v106, s[8:9]
	v_cndmask_b32_e64 v78, v104, v134, s[8:9]
	v_pk_fma_f32 v[84:85], v[84:85], v[140:141], v[164:165]
	v_pk_fma_f32 v[74:75], v[154:155], v[86:87], v[74:75]
	v_cndmask_b32_e64 v87, v102, v107, s[6:7]
	v_cndmask_b32_e64 v86, v105, v135, s[6:7]
	v_pk_fma_f32 v[78:79], v[166:167], v[78:79], v[84:85]
	v_mov_b32_e32 v108, 0
	v_pk_fma_f32 v[78:79], v[168:169], v[86:87], v[78:79]
	v_mov_b32_e32 v86, 0
	v_mov_b32_e32 v109, 0
	v_mov_b32_e32 v87, 0
	v_mov_b32_dpp v86, v77 row_ror:1 row_mask:0xf bank_mask:0xf
	v_mul_f32_e32 v84, 0xbfb8aa3b, v82
	v_mov_b32_dpp v108, v81 row_ror:1 row_mask:0xf bank_mask:0xf
	v_mov_b32_dpp v109, v81 row_ror:2 row_mask:0xf bank_mask:0xf
	v_mov_b32_e32 v80, v81
	v_mov_b32_e32 v81, v77
	v_mov_b32_dpp v87, v77 row_ror:2 row_mask:0xf bank_mask:0xf
	v_cndmask_b32_e64 v77, v86, v100, s[8:9]
	v_exp_f32_e32 v100, v84
	v_cndmask_b32_e64 v76, v108, v136, s[8:9]
	v_pk_fma_f32 v[80:81], v[80:81], v[152:153], v[132:133]
	v_cndmask_b32_e64 v85, v87, v101, s[6:7]
	v_pk_fma_f32 v[76:77], v[150:151], v[76:77], v[80:81]
	v_add_f32_e32 v80, 1.0, v100
	v_rcp_f32_e32 v80, v80
	v_mul_f32_e32 v81, 0xbfb8aa3b, v74
	v_exp_f32_e32 v81, v81
	v_cndmask_b32_e64 v84, v109, v137, s[6:7]
	v_pk_fma_f32 v[76:77], v[148:149], v[84:85], v[76:77]
	v_mul_f32_e32 v80, v82, v80
	v_mul_f32_e32 v80, v80, v83
	v_add_f32_e32 v81, 1.0, v81
	v_mul_f32_e32 v82, 0xbfb8aa3b, v78
	v_mul_f32_e32 v83, 0xbfb8aa3b, v76
	v_rcp_f32_e32 v81, v81
	v_exp_f32_e32 v82, v82
	v_exp_f32_e32 v83, v83
	v_mov_b32_e32 v84, 0
	v_mul_f32_e32 v74, v74, v81
	v_add_f32_e32 v81, 1.0, v82
	v_add_f32_e32 v82, 1.0, v83
	v_rcp_f32_e32 v81, v81
	v_rcp_f32_e32 v82, v82
	v_mul_f32_e32 v74, v74, v75
	v_cvt_pk_bf16_f32 v74, v80, v74
	v_mul_f32_e32 v75, v78, v81
	v_mul_f32_e32 v76, v76, v82
	v_mul_f32_e32 v75, v75, v79
	v_mul_f32_e32 v76, v76, v77
	v_add_u32_e32 v77, 0xa0, v188
	v_cvt_pk_bf16_f32 v75, v75, v76
	v_mad_i64_i32 v[76:77], s[38:39], v77, s72, v[90:91]
	v_lshl_add_u64 v[128:129], v[76:77], 0, v[138:139]
	v_mov_b32_e32 v78, 0
	v_mov_b32_e32 v79, 0
	global_store_dwordx2 v[128:129], v[74:75], off
	v_mov_b32_dpp v78, v70 row_ror:1 row_mask:0xf bank_mask:0xf
	v_mov_b32_e32 v74, v70
	v_mov_b32_e32 v75, v66
	v_mov_b32_dpp v79, v66 row_ror:1 row_mask:0xf bank_mask:0xf
	v_mov_b32_e32 v81, 0
	v_mov_b32_e32 v80, 0
	v_mov_b32_e32 v82, 0
	v_mov_b32_e32 v83, 0
	v_mov_b32_dpp v81, v66 row_ror:2 row_mask:0xf bank_mask:0xf
	v_cndmask_b32_e64 v79, v79, v110, s[8:9]
	v_cndmask_b32_e64 v78, v78, v92, s[8:9]
	v_pk_fma_f32 v[74:75], v[74:75], v[144:145], v[146:147]
	v_mov_b32_e32 v66, 0
	v_mov_b32_dpp v80, v70 row_ror:2 row_mask:0xf bank_mask:0xf
	v_mov_b32_dpp v82, v71 row_ror:1 row_mask:0xf bank_mask:0xf
	v_mov_b32_dpp v83, v71 row_ror:2 row_mask:0xf bank_mask:0xf
	v_mov_b32_e32 v70, v71
	v_mov_b32_e32 v71, v67
	v_pk_fma_f32 v[74:75], v[160:161], v[78:79], v[74:75]
	v_mov_b32_dpp v66, v67 row_ror:1 row_mask:0xf bank_mask:0xf
	v_mov_b32_e32 v78, 0
	v_pk_fma_f32 v[70:71], v[70:71], v[158:159], v[130:131]
	v_mov_b32_dpp v84, v72 row_ror:1 row_mask:0xf bank_mask:0xf
	v_mov_b32_dpp v78, v67 row_ror:2 row_mask:0xf bank_mask:0xf
	v_cndmask_b32_e64 v67, v66, v88, s[8:9]
	v_cndmask_b32_e64 v66, v82, v94, s[8:9]
	v_pk_fma_f32 v[66:67], v[156:157], v[66:67], v[70:71]
	v_mov_b32_e32 v70, 0
	v_mov_b32_e32 v76, v72
	v_mov_b32_e32 v77, v68
	v_mov_b32_dpp v70, v68 row_ror:1 row_mask:0xf bank_mask:0xf
	v_cndmask_b32_e64 v79, v78, v89, s[6:7]
	v_cndmask_b32_e64 v78, v83, v95, s[6:7]
	v_cndmask_b32_e64 v71, v70, v99, s[8:9]
	v_cndmask_b32_e64 v70, v84, v104, s[8:9]
	v_pk_fma_f32 v[76:77], v[76:77], v[140:141], v[164:165]
	v_mov_b32_e32 v85, 0
	v_cndmask_b32_e64 v81, v81, v111, s[6:7]
	v_cndmask_b32_e64 v80, v80, v93, s[6:7]
	v_pk_fma_f32 v[66:67], v[154:155], v[78:79], v[66:67]
	v_mov_b32_e32 v78, 0
	v_pk_fma_f32 v[70:71], v[166:167], v[70:71], v[76:77]
	v_mov_b32_e32 v76, 0
	v_mov_b32_dpp v85, v72 row_ror:2 row_mask:0xf bank_mask:0xf
	v_pk_fma_f32 v[74:75], v[162:163], v[80:81], v[74:75]
	v_mov_b32_dpp v78, v68 row_ror:2 row_mask:0xf bank_mask:0xf
	v_mov_b32_dpp v76, v69 row_ror:2 row_mask:0xf bank_mask:0xf
	v_cndmask_b32_e64 v79, v78, v102, s[6:7]
	v_cndmask_b32_e64 v78, v85, v105, s[6:7]
	v_cndmask_b32_e64 v77, v76, v87, s[6:7]
	v_mul_f32_e32 v76, 0xbfb8aa3b, v74
	v_pk_fma_f32 v[70:71], v[168:169], v[78:79], v[70:71]
	v_exp_f32_e32 v78, v76
	v_mov_b32_e32 v100, 0
	v_mov_b32_e32 v101, 0
	v_mov_b32_e32 v68, 0
	v_mov_b32_dpp v100, v73 row_ror:1 row_mask:0xf bank_mask:0xf
	v_mov_b32_dpp v101, v73 row_ror:2 row_mask:0xf bank_mask:0xf
	v_mov_b32_e32 v72, v73
	v_mov_b32_e32 v73, v69
	v_mov_b32_dpp v68, v69 row_ror:1 row_mask:0xf bank_mask:0xf
	v_cndmask_b32_e64 v69, v68, v86, s[8:9]
	v_cndmask_b32_e64 v68, v100, v108, s[8:9]
	v_pk_fma_f32 v[72:73], v[72:73], v[152:153], v[132:133]
	v_cndmask_b32_e64 v76, v101, v109, s[6:7]
	v_pk_fma_f32 v[68:69], v[150:151], v[68:69], v[72:73]
	v_add_f32_e32 v72, 1.0, v78
	v_rcp_f32_e32 v72, v72
	v_mul_f32_e32 v73, 0xbfb8aa3b, v66
	v_exp_f32_e32 v73, v73
	v_pk_fma_f32 v[68:69], v[148:149], v[76:77], v[68:69]
	v_mul_f32_e32 v72, v74, v72
	v_mul_f32_e32 v72, v72, v75
	v_add_f32_e32 v73, 1.0, v73
	v_mul_f32_e32 v74, 0xbfb8aa3b, v70
	v_mul_f32_e32 v75, 0xbfb8aa3b, v68
	v_rcp_f32_e32 v73, v73
	v_exp_f32_e32 v74, v74
	v_exp_f32_e32 v75, v75
	v_mov_b32_e32 v98, 0
	v_mul_f32_e32 v66, v66, v73
	v_add_f32_e32 v73, 1.0, v74
	v_add_f32_e32 v74, 1.0, v75
	v_rcp_f32_e32 v73, v73
	v_rcp_f32_e32 v74, v74
	v_mul_f32_e32 v66, v66, v67
	v_cvt_pk_bf16_f32 v66, v72, v66
	v_mul_f32_e32 v67, v70, v73
	v_mul_f32_e32 v68, v68, v74
	v_mul_f32_e32 v67, v67, v71
	v_mul_f32_e32 v68, v68, v69
	v_add_u32_e32 v69, 0xb0, v188
	v_cvt_pk_bf16_f32 v67, v67, v68
	v_mad_i64_i32 v[68:69], s[38:39], v69, s72, v[90:91]
	v_lshl_add_u64 v[130:131], v[68:69], 0, v[138:139]
	global_store_dwordx2 v[130:131], v[66:67], off
	v_add_co_u32_e32 v66, vcc, 0x15000, v206
	v_mov_b32_e32 v70, s94
	global_load_dwordx4 v[72:75], v[210:211], off offset:16
	global_load_dwordx4 v[80:83], v[206:207], off offset:16
	v_addc_co_u32_e32 v67, vcc, 0, v207, vcc
	v_add_co_u32_e32 v68, vcc, 0x2b000, v206
	s_nop 1
	v_addc_co_u32_e32 v69, vcc, 0, v207, vcc
	global_load_dwordx4 v[88:91], v[66:67], off offset:2064
	global_load_dwordx4 v[84:87], v[68:69], off offset:16
	v_add_co_u32_e32 v66, vcc, 0xa000, v210
	s_nop 1
	v_addc_co_u32_e32 v67, vcc, 0, v211, vcc
	v_add_co_u32_e32 v76, vcc, 0xa000, v206
	global_load_dwordx4 v[66:69], v[66:67], off offset:3088
	s_nop 0
	global_load_dwordx4 v[114:117], v[208:209], off offset:16
	global_load_dwordx4 v[92:95], v[208:209], off offset:528
	v_addc_co_u32_e32 v77, vcc, 0, v207, vcc
	v_add_co_u32_e32 v78, vcc, 0x20000, v206
	s_nop 1
	v_addc_co_u32_e32 v79, vcc, 0, v207, vcc
	global_load_dwordx4 v[106:109], v[76:77], off offset:3088
	global_load_dwordx4 v[102:105], v[78:79], off offset:1040
	v_add_co_u32_e32 v76, vcc, 0x35000, v206
	v_mov_b32_e32 v78, 0
	s_nop 0
	v_addc_co_u32_e32 v77, vcc, 0, v207, vcc
	global_load_dwordx4 v[110:113], v[76:77], off offset:3088
	v_mov_b32_e32 v76, 0
	v_mov_b32_e32 v77, 0
	v_mov_b32_e32 v79, 0
	s_and_saveexec_b64 s[38:39], s[26:27]
	ds_read_b128 v[76:79], v217
	s_or_b64 exec, exec, s[38:39]
	v_mov_b32_e32 v99, 0
	v_mov_b32_e32 v100, 0
	v_mov_b32_e32 v101, 0
	s_and_saveexec_b64 s[38:39], s[26:27]
	ds_read_b128 v[98:101], v217 offset:512
	s_or_b64 exec, exec, s[38:39]
	s_waitcnt vmcnt(4)
	v_pk_mul_f32 v[114:115], v[114:115], v[70:71] op_sel_hi:[1,0]
	v_pk_mul_f32 v[116:117], v[116:117], v[70:71] op_sel_hi:[1,0]
	v_pk_mul_f32 v[134:135], v[80:81], v[114:115]
	v_pk_mul_f32 v[138:139], v[114:115], v[88:89]
	v_pk_mul_f32 v[114:115], v[114:115], v[84:85]
	s_waitcnt vmcnt(3)
	v_pk_mul_f32 v[84:85], v[70:71], v[94:95] op_sel_hi:[0,1]
	v_pk_mul_f32 v[70:71], v[70:71], v[92:93] op_sel_hi:[0,1]
	v_pk_mul_f32 v[132:133], v[82:83], v[116:117]
	v_pk_mul_f32 v[136:137], v[116:117], v[90:91]
	v_pk_mul_f32 v[116:117], v[116:117], v[86:87]
	s_waitcnt vmcnt(2)
	v_pk_mul_f32 v[86:87], v[106:107], v[70:71]
	v_mov_b32_e32 v92, 0
	v_mov_b32_e32 v93, 0
	v_mov_b32_e32 v106, 0
	v_mov_b32_e32 v107, 0
	s_waitcnt vmcnt(1)
	v_pk_mul_f32 v[88:89], v[70:71], v[102:103]
	s_waitcnt vmcnt(0)
	v_pk_mul_f32 v[90:91], v[70:71], v[110:111]
	v_mov_b32_e32 v71, 0
	s_waitcnt lgkmcnt(0)
	v_mov_b32_dpp v92, v76 row_ror:1 row_mask:0xf bank_mask:0xf
	v_mov_b32_e32 v110, 0
	v_mov_b32_dpp v93, v76 row_ror:2 row_mask:0xf bank_mask:0xf
	v_mov_b32_dpp v106, v77 row_ror:1 row_mask:0xf bank_mask:0xf
	v_mov_b32_dpp v107, v77 row_ror:2 row_mask:0xf bank_mask:0xf
	v_mov_b32_e32 v145, 0
	v_mov_b32_e32 v76, 0
	v_mov_b32_e32 v146, 0
	v_mov_b32_e32 v77, 0
	v_pk_mul_f32 v[80:81], v[108:109], v[84:85]
	v_mov_b32_dpp v71, v62 row_ror:1 row_mask:0xf bank_mask:0xf
	v_mov_b32_dpp v110, v62 row_ror:2 row_mask:0xf bank_mask:0xf
	v_mov_b32_e32 v108, 0
	v_mov_b32_e32 v109, 0
	v_mov_b32_e32 v142, 0
	v_mov_b32_e32 v144, 0
	v_mov_b32_dpp v145, v58 row_ror:1 row_mask:0xf bank_mask:0xf
	v_mov_b32_dpp v76, v98 row_ror:1 row_mask:0xf bank_mask:0xf
	v_mov_b32_dpp v146, v58 row_ror:2 row_mask:0xf bank_mask:0xf
	v_mov_b32_dpp v77, v98 row_ror:2 row_mask:0xf bank_mask:0xf
	v_mov_b32_dpp v108, v78 row_ror:1 row_mask:0xf bank_mask:0xf
	v_mov_b32_dpp v109, v78 row_ror:2 row_mask:0xf bank_mask:0xf
	v_mov_b32_dpp v142, v79 row_ror:1 row_mask:0xf bank_mask:0xf
	v_mov_b32_dpp v144, v79 row_ror:2 row_mask:0xf bank_mask:0xf
	v_cndmask_b32_e64 v95, v145, v76, s[8:9]
	v_cndmask_b32_e64 v94, v71, v92, s[8:9]
	v_cndmask_b32_e64 v103, v146, v77, s[6:7]
	v_cndmask_b32_e64 v102, v110, v93, s[6:7]
	v_mov_b32_e32 v92, v62
	v_mov_b32_e32 v93, v58
	v_mov_b32_e32 v76, v114
	v_mov_b32_e32 v77, v90
	v_mov_b32_e32 v78, v72
	v_mov_b32_e32 v79, v66
	v_mov_b32_e32 v114, 0
	v_mov_b32_e32 v58, 0
	v_pk_mul_f32 v[82:83], v[84:85], v[104:105]
	v_mov_b32_e32 v111, 0
	v_pk_fma_f32 v[104:105], v[92:93], v[76:77], v[78:79]
	v_mov_b32_e32 v92, v138
	v_mov_b32_e32 v93, v88
	v_mov_b32_dpp v114, v59 row_ror:1 row_mask:0xf bank_mask:0xf
	v_mov_b32_dpp v58, v99 row_ror:1 row_mask:0xf bank_mask:0xf
	v_mov_b32_e32 v62, 0
	v_pk_mul_f32 v[84:85], v[84:85], v[112:113]
	v_mov_b32_dpp v111, v63 row_ror:1 row_mask:0xf bank_mask:0xf
	v_mov_b32_e32 v112, 0
	v_pk_fma_f32 v[104:105], v[92:93], v[94:95], v[104:105]
	v_mov_b32_e32 v94, v134
	v_mov_b32_e32 v134, 0
	v_mov_b32_dpp v62, v99 row_ror:2 row_mask:0xf bank_mask:0xf
	v_cndmask_b32_e64 v99, v114, v58, s[8:9]
	v_mov_b32_e32 v58, v63
	v_mov_b32_e32 v90, v115
	v_mov_b32_e32 v66, v73
	v_mov_b32_dpp v112, v63 row_ror:2 row_mask:0xf bank_mask:0xf
	v_mov_b32_e32 v95, v86
	v_mov_b32_dpp v134, v59 row_ror:2 row_mask:0xf bank_mask:0xf
	v_cndmask_b32_e64 v98, v111, v106, s[8:9]
	v_pk_fma_f32 v[58:59], v[58:59], v[90:91], v[66:67]
	v_mov_b32_e32 v88, v139
	v_pk_fma_f32 v[104:105], v[94:95], v[102:103], v[104:105]
	v_cndmask_b32_e64 v103, v134, v62, s[6:7]
	v_cndmask_b32_e64 v102, v112, v107, s[6:7]
	v_pk_fma_f32 v[58:59], v[88:89], v[98:99], v[58:59]
	v_mov_b32_e32 v86, v135
	v_mov_b32_e32 v115, 0
	v_mov_b32_e32 v135, 0
	v_mov_b32_e32 v113, 0
	v_mov_b32_e32 v140, 0
	v_pk_fma_f32 v[72:73], v[86:87], v[102:103], v[58:59]
	v_mov_b32_dpp v115, v60 row_ror:1 row_mask:0xf bank_mask:0xf
	v_mov_b32_e32 v58, 0
	v_mov_b32_dpp v135, v60 row_ror:2 row_mask:0xf bank_mask:0xf
	v_mov_b32_e32 v59, 0
	v_mov_b32_e32 v99, v60
	v_mov_b32_e32 v62, v74
	v_mov_b32_e32 v74, 0
	v_mov_b32_e32 v60, 0
	v_mov_b32_dpp v113, v64 row_ror:1 row_mask:0xf bank_mask:0xf
	v_mov_b32_dpp v140, v64 row_ror:2 row_mask:0xf bank_mask:0xf
	v_mov_b32_e32 v141, 0
	v_mov_b32_e32 v143, 0
	v_mov_b32_dpp v58, v100 row_ror:1 row_mask:0xf bank_mask:0xf
	v_mov_b32_dpp v59, v100 row_ror:2 row_mask:0xf bank_mask:0xf
	v_mov_b32_e32 v98, v64
	v_mov_b32_dpp v74, v61 row_ror:1 row_mask:0xf bank_mask:0xf
	v_mov_b32_dpp v60, v101 row_ror:1 row_mask:0xf bank_mask:0xf
	v_mov_b32_e32 v64, 0
	v_mov_b32_dpp v141, v65 row_ror:1 row_mask:0xf bank_mask:0xf
	v_mov_b32_dpp v143, v65 row_ror:2 row_mask:0xf bank_mask:0xf
	v_cndmask_b32_e64 v103, v115, v58, s[8:9]
	v_cndmask_b32_e64 v107, v135, v59, s[6:7]
	v_mov_b32_e32 v58, v116
	v_mov_b32_e32 v59, v84
	v_mov_b32_e32 v63, v68
	v_mov_b32_dpp v64, v101 row_ror:2 row_mask:0xf bank_mask:0xf
	v_cndmask_b32_e64 v101, v74, v60, s[8:9]
	v_mov_b32_e32 v60, v65
	v_mul_f32_e32 v65, 0xbfb8aa3b, v72
	v_cndmask_b32_e64 v102, v113, v108, s[8:9]
	v_cndmask_b32_e64 v106, v140, v109, s[6:7]
	v_pk_fma_f32 v[108:109], v[98:99], v[58:59], v[62:63]
	v_mov_b32_e32 v98, v136
	v_mov_b32_e32 v99, v82
	v_mov_b32_e32 v116, 0
	v_mov_b32_e32 v84, v117
	v_mov_b32_e32 v68, v75
	v_exp_f32_e32 v65, v65
	v_pk_fma_f32 v[108:109], v[98:99], v[102:103], v[108:109]
	v_mov_b32_e32 v102, v132
	v_mov_b32_e32 v103, v80
	v_mov_b32_dpp v116, v61 row_ror:2 row_mask:0xf bank_mask:0xf
	v_cndmask_b32_e64 v100, v141, v142, s[8:9]
	v_pk_fma_f32 v[60:61], v[60:61], v[84:85], v[68:69]
	v_mov_b32_e32 v82, v137
	v_pk_fma_f32 v[106:107], v[102:103], v[106:107], v[108:109]
	v_cndmask_b32_e64 v109, v116, v64, s[6:7]
	v_cndmask_b32_e64 v108, v143, v144, s[6:7]
	v_pk_fma_f32 v[60:61], v[82:83], v[100:101], v[60:61]
	v_mov_b32_e32 v80, v133
	v_pk_fma_f32 v[60:61], v[80:81], v[108:109], v[60:61]
	v_add_f32_e32 v65, 1.0, v65
	v_mul_f32_e32 v75, 0xbfb8aa3b, v106
	v_mul_f32_e32 v100, 0xbfb8aa3b, v60
	v_mul_f32_e32 v64, 0xbfb8aa3b, v104
	v_rcp_f32_e32 v65, v65
	v_exp_f32_e32 v75, v75
	v_exp_f32_e32 v100, v100
	v_exp_f32_e32 v64, v64
	v_mul_f32_e32 v65, v72, v65
	v_add_f32_e32 v72, 1.0, v75
	v_add_f32_e32 v75, 1.0, v100
	v_add_f32_e32 v64, 1.0, v64
	v_rcp_f32_e32 v72, v72
	v_rcp_f32_e32 v75, v75
	v_rcp_f32_e32 v64, v64
	v_mov_b32_e32 v109, 0
	v_mul_f32_e32 v72, v106, v72
	v_mul_f32_e32 v60, v60, v75
	v_mul_f32_e32 v64, v104, v64
	v_mul_f32_e32 v72, v72, v107
	v_mul_f32_e32 v61, v60, v61
	v_mov_b32_e32 v75, 0
	v_mul_f32_e32 v64, v64, v105
	v_mul_f32_e32 v65, v65, v73
	v_cvt_pk_bf16_f32 v60, v64, v65
	v_cvt_pk_bf16_f32 v61, v72, v61
	v_mov_b32_dpp v75, v54 row_ror:1 row_mask:0xf bank_mask:0xf
	v_mov_b32_e32 v100, 0
	v_mov_b32_dpp v109, v50 row_ror:1 row_mask:0xf bank_mask:0xf
	v_mov_b32_e32 v117, 0
	v_mov_b32_e32 v72, v54
	v_mov_b32_e32 v73, v50
	global_store_dwordx2 v[122:123], v[60:61], off offset:8
	v_mov_b32_dpp v100, v54 row_ror:2 row_mask:0xf bank_mask:0xf
	v_mov_b32_e32 v101, 0
	v_mov_b32_dpp v117, v50 row_ror:2 row_mask:0xf bank_mask:0xf
	v_cndmask_b32_e64 v61, v109, v145, s[8:9]
	v_cndmask_b32_e64 v60, v75, v71, s[8:9]
	v_pk_fma_f32 v[72:73], v[72:73], v[76:77], v[78:79]
	v_mov_b32_e32 v71, 0
	v_mov_b32_dpp v101, v55 row_ror:1 row_mask:0xf bank_mask:0xf
	v_mov_b32_e32 v104, 0
	v_cndmask_b32_e64 v65, v117, v146, s[6:7]
	v_cndmask_b32_e64 v64, v100, v110, s[6:7]
	v_pk_fma_f32 v[60:61], v[92:93], v[60:61], v[72:73]
	v_mov_b32_dpp v71, v51 row_ror:1 row_mask:0xf bank_mask:0xf
	v_mov_b32_e32 v110, 0
	v_mov_b32_e32 v50, v55
	v_mov_b32_dpp v104, v55 row_ror:2 row_mask:0xf bank_mask:0xf
	v_pk_fma_f32 v[60:61], v[94:95], v[64:65], v[60:61]
	v_mov_b32_dpp v110, v51 row_ror:2 row_mask:0xf bank_mask:0xf
	v_cndmask_b32_e64 v65, v71, v114, s[8:9]
	v_cndmask_b32_e64 v64, v101, v111, s[8:9]
	v_pk_fma_f32 v[50:51], v[50:51], v[90:91], v[66:67]
	v_mov_b32_e32 v105, 0
	v_cndmask_b32_e64 v73, v110, v134, s[6:7]
	v_cndmask_b32_e64 v72, v104, v112, s[6:7]
	v_pk_fma_f32 v[50:51], v[88:89], v[64:65], v[50:51]
	v_mov_b32_e32 v111, 0
	v_mov_b32_dpp v105, v56 row_ror:1 row_mask:0xf bank_mask:0xf
	v_mov_b32_e32 v106, 0
	v_pk_fma_f32 v[50:51], v[86:87], v[72:73], v[50:51]
	v_mov_b32_dpp v111, v52 row_ror:1 row_mask:0xf bank_mask:0xf
	v_mov_b32_e32 v112, 0
	v_mov_b32_e32 v72, v56
	v_mov_b32_e32 v73, v52
	v_mov_b32_dpp v106, v56 row_ror:2 row_mask:0xf bank_mask:0xf
	v_mov_b32_dpp v112, v52 row_ror:2 row_mask:0xf bank_mask:0xf
	v_cndmask_b32_e64 v55, v111, v115, s[8:9]
	v_cndmask_b32_e64 v54, v105, v113, s[8:9]
	v_pk_fma_f32 v[72:73], v[72:73], v[58:59], v[62:63]
	v_mov_b32_e32 v56, 0
	v_cndmask_b32_e64 v65, v112, v135, s[6:7]
	v_cndmask_b32_e64 v64, v106, v140, s[6:7]
	v_pk_fma_f32 v[54:55], v[98:99], v[54:55], v[72:73]
	v_mov_b32_dpp v56, v53 row_ror:1 row_mask:0xf bank_mask:0xf
	v_mul_f32_e32 v52, 0xbfb8aa3b, v60
	v_pk_fma_f32 v[54:55], v[102:103], v[64:65], v[54:55]
	v_cndmask_b32_e64 v65, v56, v74, s[8:9]
	v_exp_f32_e32 v74, v52
	v_mov_b32_e32 v107, 0
	v_mov_b32_e32 v108, 0
	v_mov_b32_e32 v113, 0
	v_mov_b32_dpp v107, v57 row_ror:1 row_mask:0xf bank_mask:0xf
	v_mov_b32_e32 v52, v57
	v_mov_b32_dpp v108, v57 row_ror:2 row_mask:0xf bank_mask:0xf
	v_mov_b32_dpp v113, v53 row_ror:2 row_mask:0xf bank_mask:0xf
	v_cndmask_b32_e64 v64, v107, v141, s[8:9]
	v_pk_fma_f32 v[52:53], v[52:53], v[84:85], v[68:69]
	v_add_f32_e32 v57, 1.0, v74
	v_pk_fma_f32 v[52:53], v[82:83], v[64:65], v[52:53]
	v_rcp_f32_e32 v57, v57
	v_mul_f32_e32 v64, 0xbfb8aa3b, v50
	v_exp_f32_e32 v64, v64
	v_cndmask_b32_e64 v73, v113, v116, s[6:7]
	v_cndmask_b32_e64 v72, v108, v143, s[6:7]
	v_mul_f32_e32 v57, v60, v57
	v_pk_fma_f32 v[52:53], v[80:81], v[72:73], v[52:53]
	v_mul_f32_e32 v57, v57, v61
	v_add_f32_e32 v60, 1.0, v64
	v_mul_f32_e32 v61, 0xbfb8aa3b, v54
	v_rcp_f32_e32 v60, v60
	v_exp_f32_e32 v61, v61
	v_mul_f32_e32 v64, 0xbfb8aa3b, v52
	v_exp_f32_e32 v64, v64
	v_mul_f32_e32 v50, v50, v60
	v_add_f32_e32 v60, 1.0, v61
	v_rcp_f32_e32 v60, v60
	v_add_f32_e32 v61, 1.0, v64
	v_rcp_f32_e32 v61, v61
	v_mul_f32_e32 v50, v50, v51
	v_mul_f32_e32 v51, v54, v60
	v_mul_f32_e32 v51, v51, v55
	v_mul_f32_e32 v52, v52, v61
	v_cvt_pk_bf16_f32 v50, v57, v50
	v_mov_b32_e32 v57, 0
	v_mov_b32_e32 v114, 0
	v_mul_f32_e32 v52, v52, v53
	v_cvt_pk_bf16_f32 v51, v51, v52
	v_mov_b32_dpp v57, v46 row_ror:1 row_mask:0xf bank_mask:0xf
	v_mov_b32_e32 v60, 0
	v_mov_b32_dpp v114, v42 row_ror:1 row_mask:0xf bank_mask:0xf
	v_mov_b32_e32 v115, 0
	v_mov_b32_e32 v54, v46
	v_mov_b32_e32 v55, v42
	global_store_dwordx2 v[118:119], v[50:51], off offset:8
	v_mov_b32_dpp v60, v46 row_ror:2 row_mask:0xf bank_mask:0xf
	v_mov_b32_e32 v61, 0
	v_mov_b32_dpp v115, v42 row_ror:2 row_mask:0xf bank_mask:0xf
	v_cndmask_b32_e64 v51, v114, v109, s[8:9]
	v_cndmask_b32_e64 v50, v57, v75, s[8:9]
	v_pk_fma_f32 v[54:55], v[54:55], v[76:77], v[78:79]
	v_mov_b32_e32 v75, 0
	v_mov_b32_dpp v61, v47 row_ror:1 row_mask:0xf bank_mask:0xf
	v_mov_b32_e32 v64, 0
	v_cndmask_b32_e64 v53, v115, v117, s[6:7]
	v_cndmask_b32_e64 v52, v60, v100, s[6:7]
	v_pk_fma_f32 v[50:51], v[92:93], v[50:51], v[54:55]
	v_mov_b32_dpp v75, v43 row_ror:1 row_mask:0xf bank_mask:0xf
	v_mov_b32_e32 v100, 0
	v_mov_b32_e32 v42, v47
	v_mov_b32_dpp v64, v47 row_ror:2 row_mask:0xf bank_mask:0xf
	v_pk_fma_f32 v[50:51], v[94:95], v[52:53], v[50:51]
	v_mov_b32_dpp v100, v43 row_ror:2 row_mask:0xf bank_mask:0xf
	v_cndmask_b32_e64 v53, v75, v71, s[8:9]
	v_cndmask_b32_e64 v52, v61, v101, s[8:9]
	v_pk_fma_f32 v[42:43], v[42:43], v[90:91], v[66:67]
	v_mov_b32_e32 v65, 0
	v_cndmask_b32_e64 v55, v100, v110, s[6:7]
	v_cndmask_b32_e64 v54, v64, v104, s[6:7]
	v_pk_fma_f32 v[42:43], v[88:89], v[52:53], v[42:43]
	v_mov_b32_e32 v71, 0
	v_mov_b32_dpp v65, v48 row_ror:1 row_mask:0xf bank_mask:0xf
	v_mov_b32_e32 v72, 0
	v_pk_fma_f32 v[42:43], v[86:87], v[54:55], v[42:43]
	v_mov_b32_dpp v71, v44 row_ror:1 row_mask:0xf bank_mask:0xf
	v_mov_b32_e32 v101, 0
	v_mov_b32_e32 v54, v48
	v_mov_b32_e32 v55, v44
	v_mov_b32_dpp v72, v48 row_ror:2 row_mask:0xf bank_mask:0xf
	v_mov_b32_dpp v101, v44 row_ror:2 row_mask:0xf bank_mask:0xf
	v_cndmask_b32_e64 v47, v71, v111, s[8:9]
	v_cndmask_b32_e64 v46, v65, v105, s[8:9]
	v_pk_fma_f32 v[54:55], v[54:55], v[58:59], v[62:63]
	v_mov_b32_e32 v48, 0
	v_cndmask_b32_e64 v53, v101, v112, s[6:7]
	v_cndmask_b32_e64 v52, v72, v106, s[6:7]
	v_pk_fma_f32 v[46:47], v[98:99], v[46:47], v[54:55]
	v_mov_b32_dpp v48, v45 row_ror:1 row_mask:0xf bank_mask:0xf
	v_mul_f32_e32 v44, 0xbfb8aa3b, v50
	v_pk_fma_f32 v[46:47], v[102:103], v[52:53], v[46:47]
	v_cndmask_b32_e64 v53, v48, v56, s[8:9]
	v_exp_f32_e32 v56, v44
	v_mov_b32_e32 v73, 0
	v_mov_b32_e32 v74, 0
	v_mov_b32_e32 v104, 0
	v_mov_b32_dpp v73, v49 row_ror:1 row_mask:0xf bank_mask:0xf
	v_mov_b32_e32 v44, v49
	v_mov_b32_dpp v74, v49 row_ror:2 row_mask:0xf bank_mask:0xf
	v_mov_b32_dpp v104, v45 row_ror:2 row_mask:0xf bank_mask:0xf
	v_cndmask_b32_e64 v52, v73, v107, s[8:9]
	v_pk_fma_f32 v[44:45], v[44:45], v[84:85], v[68:69]
	v_add_f32_e32 v49, 1.0, v56
	v_pk_fma_f32 v[44:45], v[82:83], v[52:53], v[44:45]
	v_rcp_f32_e32 v49, v49
	v_mul_f32_e32 v52, 0xbfb8aa3b, v42
	v_exp_f32_e32 v52, v52
	v_cndmask_b32_e64 v55, v104, v113, s[6:7]
	v_cndmask_b32_e64 v54, v74, v108, s[6:7]
	v_mul_f32_e32 v49, v50, v49
	v_pk_fma_f32 v[44:45], v[80:81], v[54:55], v[44:45]
	v_mul_f32_e32 v49, v49, v51
	v_add_f32_e32 v50, 1.0, v52
	v_mul_f32_e32 v51, 0xbfb8aa3b, v46
	v_rcp_f32_e32 v50, v50
	v_exp_f32_e32 v51, v51
	v_mul_f32_e32 v52, 0xbfb8aa3b, v44
	v_exp_f32_e32 v52, v52
	v_mul_f32_e32 v42, v42, v50
	v_add_f32_e32 v50, 1.0, v51
	v_rcp_f32_e32 v50, v50
	v_add_f32_e32 v51, 1.0, v52
	v_rcp_f32_e32 v51, v51
	v_mul_f32_e32 v42, v42, v43
	v_mul_f32_e32 v43, v46, v50
	v_mul_f32_e32 v43, v43, v47
	v_mul_f32_e32 v44, v44, v51
	v_mul_f32_e32 v44, v44, v45
	v_cvt_pk_bf16_f32 v42, v49, v42
	v_cvt_pk_bf16_f32 v43, v43, v44
	global_store_dwordx2 v[120:121], v[42:43], off offset:8
	v_mov_b32_e32 v42, 0
	v_mov_b32_e32 v43, 0
	v_mov_b32_e32 v44, 0
	v_mov_b32_dpp v42, v38 row_ror:1 row_mask:0xf bank_mask:0xf
	v_mov_b32_dpp v43, v34 row_ror:1 row_mask:0xf bank_mask:0xf
	v_mov_b32_e32 v45, 0
	v_mov_b32_e32 v46, v38
	v_mov_b32_e32 v47, v34
	v_mov_b32_dpp v44, v38 row_ror:2 row_mask:0xf bank_mask:0xf
	v_mov_b32_dpp v45, v34 row_ror:2 row_mask:0xf bank_mask:0xf
	v_cndmask_b32_e64 v43, v43, v114, s[8:9]
	v_cndmask_b32_e64 v42, v42, v57, s[8:9]
	v_pk_fma_f32 v[46:47], v[46:47], v[76:77], v[78:79]
	v_mov_b32_e32 v34, 0
	v_mov_b32_e32 v49, 0
	v_cndmask_b32_e64 v45, v45, v115, s[6:7]
	v_cndmask_b32_e64 v44, v44, v60, s[6:7]
	v_pk_fma_f32 v[42:43], v[92:93], v[42:43], v[46:47]
	v_mov_b32_dpp v34, v35 row_ror:1 row_mask:0xf bank_mask:0xf
	v_mov_b32_dpp v49, v39 row_ror:1 row_mask:0xf bank_mask:0xf
	v_mov_b32_e32 v50, 0
	v_pk_fma_f32 v[42:43], v[94:95], v[44:45], v[42:43]
	v_mov_b32_e32 v38, 0
	v_cndmask_b32_e64 v45, v34, v75, s[8:9]
	v_mov_b32_e32 v34, v39
	v_mov_b32_dpp v50, v39 row_ror:2 row_mask:0xf bank_mask:0xf
	v_mov_b32_dpp v38, v35 row_ror:2 row_mask:0xf bank_mask:0xf
	v_cndmask_b32_e64 v44, v49, v61, s[8:9]
	v_pk_fma_f32 v[34:35], v[34:35], v[90:91], v[66:67]
	v_mov_b32_e32 v51, 0
	v_cndmask_b32_e64 v47, v38, v100, s[6:7]
	v_cndmask_b32_e64 v46, v50, v64, s[6:7]
	v_pk_fma_f32 v[34:35], v[88:89], v[44:45], v[34:35]
	v_mov_b32_e32 v38, 0
	v_mov_b32_dpp v51, v40 row_ror:1 row_mask:0xf bank_mask:0xf
	v_mov_b32_e32 v52, 0
	v_pk_fma_f32 v[34:35], v[86:87], v[46:47], v[34:35]
	v_mov_b32_dpp v38, v36 row_ror:1 row_mask:0xf bank_mask:0xf
	v_mov_b32_e32 v44, 0
	v_mov_b32_e32 v46, v40
	v_mov_b32_e32 v47, v36
	v_mov_b32_dpp v52, v40 row_ror:2 row_mask:0xf bank_mask:0xf
	v_mov_b32_dpp v44, v36 row_ror:2 row_mask:0xf bank_mask:0xf
	v_cndmask_b32_e64 v39, v38, v71, s[8:9]
	v_cndmask_b32_e64 v38, v51, v65, s[8:9]
	v_pk_fma_f32 v[46:47], v[46:47], v[58:59], v[62:63]
	v_mov_b32_e32 v36, 0
	v_cndmask_b32_e64 v45, v44, v101, s[6:7]
	v_cndmask_b32_e64 v44, v52, v72, s[6:7]
	v_pk_fma_f32 v[38:39], v[98:99], v[38:39], v[46:47]
	v_mov_b32_dpp v36, v37 row_ror:1 row_mask:0xf bank_mask:0xf
	v_mov_b32_e32 v40, 0
	v_pk_fma_f32 v[38:39], v[102:103], v[44:45], v[38:39]
	v_cndmask_b32_e64 v45, v36, v48, s[8:9]
	v_mov_b32_dpp v40, v37 row_ror:2 row_mask:0xf bank_mask:0xf
	v_mul_f32_e32 v36, 0xbfb8aa3b, v42
	v_cndmask_b32_e64 v47, v40, v104, s[6:7]
	v_exp_f32_e32 v40, v36
	v_mov_b32_e32 v53, 0
	v_mov_b32_e32 v54, 0
	v_mov_b32_e32 v36, v41
	v_mov_b32_dpp v53, v41 row_ror:1 row_mask:0xf bank_mask:0xf
	v_mov_b32_dpp v54, v41 row_ror:2 row_mask:0xf bank_mask:0xf
	v_add_f32_e32 v40, 1.0, v40
	v_mul_f32_e32 v41, 0xbfb8aa3b, v34
	v_rcp_f32_e32 v40, v40
	v_exp_f32_e32 v41, v41
	v_cndmask_b32_e64 v44, v53, v73, s[8:9]
	v_pk_fma_f32 v[36:37], v[36:37], v[84:85], v[68:69]
	v_cndmask_b32_e64 v46, v54, v74, s[6:7]
	v_pk_fma_f32 v[36:37], v[82:83], v[44:45], v[36:37]
	v_mul_f32_e32 v40, v42, v40
	v_pk_fma_f32 v[36:37], v[80:81], v[46:47], v[36:37]
	v_add_f32_e32 v41, 1.0, v41
	v_mul_f32_e32 v42, 0xbfb8aa3b, v38
	v_mul_f32_e32 v40, v40, v43
	v_rcp_f32_e32 v41, v41
	v_exp_f32_e32 v42, v42
	v_mul_f32_e32 v43, 0xbfb8aa3b, v36
	v_exp_f32_e32 v43, v43
	v_mul_f32_e32 v34, v34, v41
	v_add_f32_e32 v41, 1.0, v42
	v_rcp_f32_e32 v41, v41
	v_add_f32_e32 v42, 1.0, v43
	v_rcp_f32_e32 v42, v42
	v_mul_f32_e32 v34, v34, v35
	v_mul_f32_e32 v35, v38, v41
	v_mul_f32_e32 v35, v35, v39
	v_mul_f32_e32 v36, v36, v42
	v_mul_f32_e32 v36, v36, v37
	v_cvt_pk_bf16_f32 v34, v40, v34
	v_cvt_pk_bf16_f32 v35, v35, v36
	global_store_dwordx2 v[124:125], v[34:35], off offset:8
	v_mov_b32_e32 v70, 0
	v_mov_b32_e32 v34, 0
	v_mov_b32_e32 v35, 0
	v_mov_b32_e32 v36, 0
	v_mov_b32_e32 v37, 0
	s_and_saveexec_b64 s[38:39], s[4:5]
	ds_read_b128 v[34:37], v218
	s_or_b64 exec, exec, s[38:39]
	v_mov_b32_e32 v71, 0
	v_mov_b32_e32 v72, 0
	v_mov_b32_e32 v73, 0
	s_and_saveexec_b64 s[38:39], s[4:5]
	ds_read_b128 v[70:73], v218 offset:512
	s_or_b64 exec, exec, s[38:39]
	v_mov_b32_e32 v50, 0
	v_mov_b32_e32 v52, 0
	v_mov_b32_e32 v42, 0
	v_mov_b32_e32 v40, 0
	s_waitcnt lgkmcnt(0)
	v_mov_b32_dpp v50, v36 row_ror:1 row_mask:0xf bank_mask:0xf
	v_mov_b32_dpp v52, v36 row_ror:2 row_mask:0xf bank_mask:0xf
	v_mov_b32_e32 v57, 0
	v_mov_b32_e32 v36, 0
	v_mov_b32_e32 v60, 0
	v_mov_b32_dpp v42, v30 row_ror:1 row_mask:0xf bank_mask:0xf
	v_mov_b32_dpp v40, v34 row_ror:1 row_mask:0xf bank_mask:0xf
	v_mov_b32_e32 v43, 0
	v_mov_b32_e32 v44, 0
	v_mov_b32_e32 v38, v30
	v_mov_b32_e32 v39, v26
	v_mov_b32_e32 v54, 0
	v_mov_b32_e32 v56, 0
	v_mov_b32_dpp v57, v26 row_ror:1 row_mask:0xf bank_mask:0xf
	v_mov_b32_dpp v36, v70 row_ror:1 row_mask:0xf bank_mask:0xf
	v_mov_b32_dpp v60, v26 row_ror:2 row_mask:0xf bank_mask:0xf
	v_mov_b32_e32 v26, 0
	v_mov_b32_dpp v43, v30 row_ror:2 row_mask:0xf bank_mask:0xf
	v_mov_b32_dpp v44, v34 row_ror:2 row_mask:0xf bank_mask:0xf
	v_mov_b32_dpp v54, v37 row_ror:1 row_mask:0xf bank_mask:0xf
	v_mov_b32_dpp v56, v37 row_ror:2 row_mask:0xf bank_mask:0xf
	v_mov_b32_dpp v26, v70 row_ror:2 row_mask:0xf bank_mask:0xf
	v_cndmask_b32_e64 v37, v57, v36, s[8:9]
	v_cndmask_b32_e64 v36, v42, v40, s[8:9]
	v_pk_fma_f32 v[38:39], v[38:39], v[76:77], v[78:79]
	v_cndmask_b32_e64 v41, v60, v26, s[6:7]
	v_cndmask_b32_e64 v40, v43, v44, s[6:7]
	v_pk_fma_f32 v[36:37], v[92:93], v[36:37], v[38:39]
	v_mov_b32_e32 v45, 0
	v_mov_b32_e32 v46, 0
	v_mov_b32_e32 v47, 0
	v_pk_fma_f32 v[36:37], v[94:95], v[40:41], v[36:37]
	v_mov_b32_e32 v40, 0
	v_mov_b32_e32 v26, 0
	v_mov_b32_dpp v45, v31 row_ror:1 row_mask:0xf bank_mask:0xf
	v_mov_b32_dpp v46, v35 row_ror:1 row_mask:0xf bank_mask:0xf
	v_mov_b32_dpp v47, v31 row_ror:2 row_mask:0xf bank_mask:0xf
	v_mov_b32_e32 v30, v31
	v_mov_b32_e32 v31, v27
	v_mov_b32_dpp v40, v27 row_ror:1 row_mask:0xf bank_mask:0xf
	v_mov_b32_dpp v26, v71 row_ror:1 row_mask:0xf bank_mask:0xf
	v_mov_b32_e32 v41, 0
	v_pk_fma_f32 v[30:31], v[30:31], v[90:91], v[66:67]
	v_mov_b32_e32 v48, 0
	v_mov_b32_dpp v41, v27 row_ror:2 row_mask:0xf bank_mask:0xf
	v_cndmask_b32_e64 v27, v40, v26, s[8:9]
	v_cndmask_b32_e64 v26, v45, v46, s[8:9]
	v_mov_b32_e32 v49, 0
	v_mov_b32_e32 v38, 0
	v_pk_fma_f32 v[26:27], v[88:89], v[26:27], v[30:31]
	v_mov_b32_e32 v44, 0
	v_mov_b32_e32 v30, 0
	v_mov_b32_e32 v46, 0
	v_mov_b32_dpp v48, v35 row_ror:2 row_mask:0xf bank_mask:0xf
	v_mov_b32_dpp v49, v32 row_ror:1 row_mask:0xf bank_mask:0xf
	v_mov_b32_e32 v51, 0
	v_mov_b32_e32 v34, v32
	v_mov_b32_e32 v35, v28
	v_mov_b32_dpp v38, v71 row_ror:2 row_mask:0xf bank_mask:0xf
	v_mov_b32_dpp v44, v28 row_ror:1 row_mask:0xf bank_mask:0xf
	v_mov_b32_dpp v30, v72 row_ror:1 row_mask:0xf bank_mask:0xf
	v_mov_b32_dpp v46, v28 row_ror:2 row_mask:0xf bank_mask:0xf
	v_mov_b32_e32 v28, 0
	v_mov_b32_dpp v51, v32 row_ror:2 row_mask:0xf bank_mask:0xf
	v_cndmask_b32_e64 v39, v41, v38, s[6:7]
	v_cndmask_b32_e64 v38, v47, v48, s[6:7]
	v_mov_b32_dpp v28, v72 row_ror:2 row_mask:0xf bank_mask:0xf
	v_cndmask_b32_e64 v31, v44, v30, s[8:9]
	v_cndmask_b32_e64 v30, v49, v50, s[8:9]
	v_pk_fma_f32 v[34:35], v[34:35], v[58:59], v[62:63]
	v_pk_fma_f32 v[26:27], v[86:87], v[38:39], v[26:27]
	v_cndmask_b32_e64 v39, v46, v28, s[6:7]
	v_cndmask_b32_e64 v38, v51, v52, s[6:7]
	v_pk_fma_f32 v[30:31], v[98:99], v[30:31], v[34:35]
	v_mov_b32_e32 v53, 0
	v_mov_b32_e32 v55, 0
	v_pk_fma_f32 v[30:31], v[102:103], v[38:39], v[30:31]
	v_mov_b32_e32 v38, 0
	v_mov_b32_e32 v28, 0
	v_mov_b32_dpp v53, v33 row_ror:1 row_mask:0xf bank_mask:0xf
	v_mov_b32_dpp v55, v33 row_ror:2 row_mask:0xf bank_mask:0xf
	v_mov_b32_e32 v32, v33
	v_mov_b32_e32 v33, v29
	v_mov_b32_dpp v38, v29 row_ror:1 row_mask:0xf bank_mask:0xf
	v_mov_b32_dpp v28, v73 row_ror:1 row_mask:0xf bank_mask:0xf
	v_mov_b32_e32 v39, 0
	v_pk_fma_f32 v[32:33], v[32:33], v[84:85], v[68:69]
	v_mov_b32_e32 v34, 0
	v_mov_b32_dpp v39, v29 row_ror:2 row_mask:0xf bank_mask:0xf
	v_cndmask_b32_e64 v29, v38, v28, s[8:9]
	v_cndmask_b32_e64 v28, v53, v54, s[8:9]
	v_pk_fma_f32 v[28:29], v[82:83], v[28:29], v[32:33]
	v_mul_f32_e32 v33, 0xbfb8aa3b, v26
	v_exp_f32_e32 v33, v33
	v_mov_b32_dpp v34, v73 row_ror:2 row_mask:0xf bank_mask:0xf
	v_cndmask_b32_e64 v35, v39, v34, s[6:7]
	v_mul_f32_e32 v34, 0xbfb8aa3b, v36
	v_exp_f32_e32 v48, v34
	v_cndmask_b32_e64 v34, v55, v56, s[6:7]
	v_pk_fma_f32 v[28:29], v[80:81], v[34:35], v[28:29]
	v_add_f32_e32 v33, 1.0, v33
	v_mul_f32_e32 v34, 0xbfb8aa3b, v30
	v_rcp_f32_e32 v33, v33
	v_exp_f32_e32 v34, v34
	v_mul_f32_e32 v35, 0xbfb8aa3b, v28
	v_exp_f32_e32 v35, v35
	v_mul_f32_e32 v26, v26, v33
	v_add_f32_e32 v33, 1.0, v34
	v_add_f32_e32 v32, 1.0, v48
	v_rcp_f32_e32 v33, v33
	v_add_f32_e32 v34, 1.0, v35
	v_rcp_f32_e32 v32, v32
	v_rcp_f32_e32 v34, v34
	v_mul_f32_e32 v26, v26, v27
	v_mul_f32_e32 v27, v30, v33
	v_mul_f32_e32 v32, v36, v32
	v_mul_f32_e32 v27, v27, v31
	v_mul_f32_e32 v28, v28, v34
	v_mul_f32_e32 v32, v32, v37
	v_mul_f32_e32 v28, v28, v29
	v_cvt_pk_bf16_f32 v26, v32, v26
	v_cvt_pk_bf16_f32 v27, v27, v28
	v_mov_b32_e32 v34, 0
	v_mov_b32_e32 v56, 0
	global_store_dwordx2 v[96:97], v[26:27], off offset:8
	v_mov_b32_dpp v34, v22 row_ror:1 row_mask:0xf bank_mask:0xf
	v_mov_b32_e32 v35, 0
	v_mov_b32_e32 v26, v22
	v_mov_b32_e32 v27, v18
	v_mov_b32_dpp v56, v18 row_ror:1 row_mask:0xf bank_mask:0xf
	v_mov_b32_e32 v61, 0
	v_mov_b32_dpp v35, v22 row_ror:2 row_mask:0xf bank_mask:0xf
	v_cndmask_b32_e64 v31, v56, v57, s[8:9]
	v_mov_b32_dpp v61, v18 row_ror:2 row_mask:0xf bank_mask:0xf
	v_cndmask_b32_e64 v30, v34, v42, s[8:9]
	v_pk_fma_f32 v[26:27], v[26:27], v[76:77], v[78:79]
	v_cndmask_b32_e64 v33, v61, v60, s[6:7]
	v_cndmask_b32_e64 v32, v35, v43, s[6:7]
	v_pk_fma_f32 v[26:27], v[92:93], v[30:31], v[26:27]
	v_mov_b32_e32 v36, 0
	v_pk_fma_f32 v[26:27], v[94:95], v[32:33], v[26:27]
	v_mov_b32_e32 v32, 0
	v_mov_b32_e32 v37, 0
	v_mov_b32_e32 v33, 0
	v_mov_b32_dpp v32, v19 row_ror:1 row_mask:0xf bank_mask:0xf
	v_mov_b32_dpp v36, v23 row_ror:1 row_mask:0xf bank_mask:0xf
	v_mov_b32_dpp v37, v23 row_ror:2 row_mask:0xf bank_mask:0xf
	v_mov_b32_e32 v22, v23
	v_mov_b32_e32 v23, v19
	v_mov_b32_e32 v48, 0
	v_mov_b32_dpp v33, v19 row_ror:2 row_mask:0xf bank_mask:0xf
	v_cndmask_b32_e64 v19, v32, v40, s[8:9]
	v_mov_b32_e32 v40, 0
	v_mov_b32_dpp v48, v24 row_ror:1 row_mask:0xf bank_mask:0xf
	v_mov_b32_e32 v50, 0
	v_mov_b32_e32 v28, v24
	v_mov_b32_e32 v29, v20
	v_cndmask_b32_e64 v18, v36, v45, s[8:9]
	v_cndmask_b32_e64 v31, v33, v41, s[6:7]
	v_pk_fma_f32 v[22:23], v[22:23], v[90:91], v[66:67]
	v_mov_b32_dpp v40, v20 row_ror:1 row_mask:0xf bank_mask:0xf
	v_mov_b32_e32 v41, 0
	v_mov_b32_dpp v50, v24 row_ror:2 row_mask:0xf bank_mask:0xf
	v_cndmask_b32_e64 v30, v37, v47, s[6:7]
	v_pk_fma_f32 v[18:19], v[88:89], v[18:19], v[22:23]
	v_mov_b32_dpp v41, v20 row_ror:2 row_mask:0xf bank_mask:0xf
	v_cndmask_b32_e64 v23, v40, v44, s[8:9]
	v_cndmask_b32_e64 v22, v48, v49, s[8:9]
	v_pk_fma_f32 v[28:29], v[28:29], v[58:59], v[62:63]
	v_pk_fma_f32 v[18:19], v[86:87], v[30:31], v[18:19]
	v_cndmask_b32_e64 v31, v41, v46, s[6:7]
	v_cndmask_b32_e64 v30, v50, v51, s[6:7]
	v_pk_fma_f32 v[22:23], v[98:99], v[22:23], v[28:29]
	v_mov_b32_e32 v52, 0
	v_pk_fma_f32 v[22:23], v[102:103], v[30:31], v[22:23]
	v_mov_b32_e32 v30, 0
	v_mov_b32_e32 v54, 0
	v_mov_b32_e32 v31, 0
	v_mov_b32_dpp v30, v21 row_ror:1 row_mask:0xf bank_mask:0xf
	v_mul_f32_e32 v28, 0xbfb8aa3b, v26
	v_mov_b32_dpp v52, v25 row_ror:1 row_mask:0xf bank_mask:0xf
	v_mov_b32_dpp v54, v25 row_ror:2 row_mask:0xf bank_mask:0xf
	v_mov_b32_e32 v24, v25
	v_mov_b32_e32 v25, v21
	v_mov_b32_dpp v31, v21 row_ror:2 row_mask:0xf bank_mask:0xf
	v_cndmask_b32_e64 v21, v30, v38, s[8:9]
	v_exp_f32_e32 v38, v28
	v_cndmask_b32_e64 v20, v52, v53, s[8:9]
	v_pk_fma_f32 v[24:25], v[24:25], v[84:85], v[68:69]
	v_cndmask_b32_e64 v29, v31, v39, s[6:7]
	v_pk_fma_f32 v[20:21], v[82:83], v[20:21], v[24:25]
	v_add_f32_e32 v24, 1.0, v38
	v_mul_f32_e32 v25, 0xbfb8aa3b, v18
	v_rcp_f32_e32 v24, v24
	v_exp_f32_e32 v25, v25
	v_cndmask_b32_e64 v28, v54, v55, s[6:7]
	v_pk_fma_f32 v[20:21], v[80:81], v[28:29], v[20:21]
	v_mul_f32_e32 v24, v26, v24
	v_add_f32_e32 v25, 1.0, v25
	v_mul_f32_e32 v26, 0xbfb8aa3b, v22
	v_mul_f32_e32 v24, v24, v27
	v_rcp_f32_e32 v25, v25
	v_exp_f32_e32 v26, v26
	v_mul_f32_e32 v27, 0xbfb8aa3b, v20
	v_exp_f32_e32 v27, v27
	v_mul_f32_e32 v18, v18, v25
	v_add_f32_e32 v25, 1.0, v26
	v_rcp_f32_e32 v25, v25
	v_add_f32_e32 v26, 1.0, v27
	v_rcp_f32_e32 v26, v26
	v_mul_f32_e32 v18, v18, v19
	v_mul_f32_e32 v19, v22, v25
	v_mul_f32_e32 v19, v19, v23
	v_mul_f32_e32 v20, v20, v26
	v_mul_f32_e32 v20, v20, v21
	v_cvt_pk_bf16_f32 v18, v24, v18
	v_cvt_pk_bf16_f32 v19, v19, v20
	v_mov_b32_e32 v26, 0
	v_mov_b32_e32 v44, 0
	global_store_dwordx2 v[126:127], v[18:19], off offset:8
	v_mov_b32_dpp v26, v14 row_ror:1 row_mask:0xf bank_mask:0xf
	v_mov_b32_e32 v27, 0
	v_mov_b32_e32 v18, v14
	v_mov_b32_e32 v19, v10
	v_mov_b32_dpp v44, v10 row_ror:1 row_mask:0xf bank_mask:0xf
	v_mov_b32_e32 v45, 0
	v_mov_b32_dpp v27, v14 row_ror:2 row_mask:0xf bank_mask:0xf
	v_cndmask_b32_e64 v23, v44, v56, s[8:9]
	v_mov_b32_dpp v45, v10 row_ror:2 row_mask:0xf bank_mask:0xf
	v_cndmask_b32_e64 v22, v26, v34, s[8:9]
	v_pk_fma_f32 v[18:19], v[18:19], v[76:77], v[78:79]
	v_cndmask_b32_e64 v25, v45, v61, s[6:7]
	v_cndmask_b32_e64 v24, v27, v35, s[6:7]
	v_pk_fma_f32 v[18:19], v[92:93], v[22:23], v[18:19]
	v_mov_b32_e32 v28, 0
	v_pk_fma_f32 v[18:19], v[94:95], v[24:25], v[18:19]
	v_mov_b32_e32 v24, 0
	v_mov_b32_e32 v29, 0
	v_mov_b32_e32 v25, 0
	v_mov_b32_dpp v24, v11 row_ror:1 row_mask:0xf bank_mask:0xf
	v_mov_b32_dpp v28, v15 row_ror:1 row_mask:0xf bank_mask:0xf
	v_mov_b32_dpp v29, v15 row_ror:2 row_mask:0xf bank_mask:0xf
	v_mov_b32_e32 v14, v15
	v_mov_b32_e32 v15, v11
	v_mov_b32_e32 v38, 0
	v_mov_b32_dpp v25, v11 row_ror:2 row_mask:0xf bank_mask:0xf
	v_cndmask_b32_e64 v11, v24, v32, s[8:9]
	v_mov_b32_e32 v32, 0
	v_mov_b32_dpp v38, v16 row_ror:1 row_mask:0xf bank_mask:0xf
	v_mov_b32_e32 v39, 0
	v_mov_b32_e32 v20, v16
	v_mov_b32_e32 v21, v12
	v_cndmask_b32_e64 v10, v28, v36, s[8:9]
	v_cndmask_b32_e64 v23, v25, v33, s[6:7]
	v_pk_fma_f32 v[14:15], v[14:15], v[90:91], v[66:67]
	v_mov_b32_dpp v32, v12 row_ror:1 row_mask:0xf bank_mask:0xf
	v_mov_b32_e32 v33, 0
	v_mov_b32_dpp v39, v16 row_ror:2 row_mask:0xf bank_mask:0xf
	v_cndmask_b32_e64 v22, v29, v37, s[6:7]
	v_pk_fma_f32 v[10:11], v[88:89], v[10:11], v[14:15]
	v_mov_b32_dpp v33, v12 row_ror:2 row_mask:0xf bank_mask:0xf
	v_cndmask_b32_e64 v15, v32, v40, s[8:9]
	v_cndmask_b32_e64 v14, v38, v48, s[8:9]
	v_pk_fma_f32 v[20:21], v[20:21], v[58:59], v[62:63]
	v_pk_fma_f32 v[10:11], v[86:87], v[22:23], v[10:11]
	v_cndmask_b32_e64 v23, v33, v41, s[6:7]
	v_cndmask_b32_e64 v22, v39, v50, s[6:7]
	v_pk_fma_f32 v[14:15], v[98:99], v[14:15], v[20:21]
	v_mov_b32_e32 v42, 0
	v_pk_fma_f32 v[14:15], v[102:103], v[22:23], v[14:15]
	v_mov_b32_e32 v22, 0
	v_mov_b32_e32 v43, 0
	v_mov_b32_e32 v23, 0
	v_mov_b32_dpp v22, v13 row_ror:1 row_mask:0xf bank_mask:0xf
	v_mul_f32_e32 v20, 0xbfb8aa3b, v18
	v_mov_b32_dpp v42, v17 row_ror:1 row_mask:0xf bank_mask:0xf
	v_mov_b32_dpp v43, v17 row_ror:2 row_mask:0xf bank_mask:0xf
	v_mov_b32_e32 v16, v17
	v_mov_b32_e32 v17, v13
	v_mov_b32_dpp v23, v13 row_ror:2 row_mask:0xf bank_mask:0xf
	v_cndmask_b32_e64 v13, v22, v30, s[8:9]
	v_exp_f32_e32 v30, v20
	v_cndmask_b32_e64 v12, v42, v52, s[8:9]
	v_pk_fma_f32 v[16:17], v[16:17], v[84:85], v[68:69]
	v_cndmask_b32_e64 v21, v23, v31, s[6:7]
	v_pk_fma_f32 v[12:13], v[82:83], v[12:13], v[16:17]
	v_add_f32_e32 v16, 1.0, v30
	v_mul_f32_e32 v17, 0xbfb8aa3b, v10
	v_rcp_f32_e32 v16, v16
	v_exp_f32_e32 v17, v17
	v_cndmask_b32_e64 v20, v43, v54, s[6:7]
	v_pk_fma_f32 v[12:13], v[80:81], v[20:21], v[12:13]
	v_mul_f32_e32 v16, v18, v16
	v_add_f32_e32 v17, 1.0, v17
	v_mul_f32_e32 v18, 0xbfb8aa3b, v14
	v_mul_f32_e32 v16, v16, v19
	v_rcp_f32_e32 v17, v17
	v_exp_f32_e32 v18, v18
	v_mul_f32_e32 v19, 0xbfb8aa3b, v12
	v_exp_f32_e32 v19, v19
	v_mul_f32_e32 v10, v10, v17
	v_add_f32_e32 v17, 1.0, v18
	v_rcp_f32_e32 v17, v17
	v_add_f32_e32 v18, 1.0, v19
	v_rcp_f32_e32 v18, v18
	v_mul_f32_e32 v10, v10, v11
	v_mul_f32_e32 v11, v14, v17
	v_mul_f32_e32 v11, v11, v15
	v_mul_f32_e32 v12, v12, v18
	v_mul_f32_e32 v12, v12, v13
	v_cvt_pk_bf16_f32 v10, v16, v10
	v_cvt_pk_bf16_f32 v11, v11, v12
	v_mov_b32_e32 v14, 0
	v_mov_b32_e32 v15, 0
	global_store_dwordx2 v[128:129], v[10:11], off offset:8
	v_mov_b32_dpp v14, v6 row_ror:1 row_mask:0xf bank_mask:0xf
	v_mov_b32_e32 v10, v6
	v_mov_b32_e32 v11, v2
	v_mov_b32_dpp v15, v2 row_ror:1 row_mask:0xf bank_mask:0xf
	v_mov_b32_e32 v17, 0
	v_mov_b32_e32 v16, 0
	v_mov_b32_e32 v18, 0
	v_mov_b32_e32 v19, 0
	v_mov_b32_dpp v17, v2 row_ror:2 row_mask:0xf bank_mask:0xf
	v_cndmask_b32_e64 v15, v15, v44, s[8:9]
	v_cndmask_b32_e64 v14, v14, v26, s[8:9]
	v_pk_fma_f32 v[10:11], v[10:11], v[76:77], v[78:79]
	v_mov_b32_e32 v2, 0
	v_mov_b32_dpp v16, v6 row_ror:2 row_mask:0xf bank_mask:0xf
	v_mov_b32_dpp v18, v7 row_ror:1 row_mask:0xf bank_mask:0xf
	v_mov_b32_dpp v19, v7 row_ror:2 row_mask:0xf bank_mask:0xf
	v_mov_b32_e32 v6, v7
	v_mov_b32_e32 v7, v3
	v_pk_fma_f32 v[10:11], v[92:93], v[14:15], v[10:11]
	v_mov_b32_dpp v2, v3 row_ror:1 row_mask:0xf bank_mask:0xf
	v_mov_b32_e32 v14, 0
	v_pk_fma_f32 v[6:7], v[6:7], v[90:91], v[66:67]
	v_mov_b32_e32 v20, 0
	v_mov_b32_dpp v14, v3 row_ror:2 row_mask:0xf bank_mask:0xf
	v_cndmask_b32_e64 v3, v2, v24, s[8:9]
	v_cndmask_b32_e64 v2, v18, v28, s[8:9]
	v_pk_fma_f32 v[2:3], v[88:89], v[2:3], v[6:7]
	v_mov_b32_e32 v6, 0
	v_mov_b32_dpp v20, v8 row_ror:1 row_mask:0xf bank_mask:0xf
	v_mov_b32_e32 v12, v8
	v_mov_b32_e32 v13, v4
	v_mov_b32_dpp v6, v4 row_ror:1 row_mask:0xf bank_mask:0xf
	v_cndmask_b32_e64 v15, v14, v25, s[6:7]
	v_cndmask_b32_e64 v14, v19, v29, s[6:7]
	v_cndmask_b32_e64 v7, v6, v32, s[8:9]
	v_cndmask_b32_e64 v6, v20, v38, s[8:9]
	v_pk_fma_f32 v[12:13], v[12:13], v[58:59], v[62:63]
	v_mov_b32_e32 v21, 0
	v_cndmask_b32_e64 v17, v17, v45, s[6:7]
	v_cndmask_b32_e64 v16, v16, v27, s[6:7]
	v_pk_fma_f32 v[2:3], v[86:87], v[14:15], v[2:3]
	v_mov_b32_e32 v14, 0
	v_pk_fma_f32 v[6:7], v[98:99], v[6:7], v[12:13]
	v_mov_b32_e32 v12, 0
	v_mov_b32_dpp v21, v8 row_ror:2 row_mask:0xf bank_mask:0xf
	v_pk_fma_f32 v[10:11], v[94:95], v[16:17], v[10:11]
	v_mov_b32_dpp v14, v4 row_ror:2 row_mask:0xf bank_mask:0xf
	v_mov_b32_dpp v12, v5 row_ror:2 row_mask:0xf bank_mask:0xf
	v_cndmask_b32_e64 v15, v14, v33, s[6:7]
	v_cndmask_b32_e64 v14, v21, v39, s[6:7]
	v_cndmask_b32_e64 v13, v12, v23, s[6:7]
	v_mul_f32_e32 v12, 0xbfb8aa3b, v10
	v_pk_fma_f32 v[6:7], v[102:103], v[14:15], v[6:7]
	v_exp_f32_e32 v14, v12
	v_mov_b32_e32 v30, 0
	v_mov_b32_e32 v31, 0
	v_mov_b32_e32 v4, 0
	v_mov_b32_dpp v30, v9 row_ror:1 row_mask:0xf bank_mask:0xf
	v_mov_b32_dpp v31, v9 row_ror:2 row_mask:0xf bank_mask:0xf
	v_mov_b32_e32 v8, v9
	v_mov_b32_e32 v9, v5
	v_mov_b32_dpp v4, v5 row_ror:1 row_mask:0xf bank_mask:0xf
	v_cndmask_b32_e64 v5, v4, v22, s[8:9]
	v_cndmask_b32_e64 v4, v30, v42, s[8:9]
	v_pk_fma_f32 v[8:9], v[8:9], v[84:85], v[68:69]
	v_cndmask_b32_e64 v12, v31, v43, s[6:7]
	v_pk_fma_f32 v[4:5], v[82:83], v[4:5], v[8:9]
	v_add_f32_e32 v8, 1.0, v14
	v_mul_f32_e32 v9, 0xbfb8aa3b, v2
	v_rcp_f32_e32 v8, v8
	v_exp_f32_e32 v9, v9
	v_pk_fma_f32 v[4:5], v[80:81], v[12:13], v[4:5]
	s_andn2_b64 vcc, exec, s[10:11]
	v_mul_f32_e32 v8, v10, v8
	v_add_f32_e32 v9, 1.0, v9
	v_mul_f32_e32 v10, 0xbfb8aa3b, v6
	v_mul_f32_e32 v8, v8, v11
	v_rcp_f32_e32 v9, v9
	v_exp_f32_e32 v10, v10
	v_mul_f32_e32 v11, 0xbfb8aa3b, v4
	v_exp_f32_e32 v11, v11
	v_mul_f32_e32 v2, v2, v9
	v_add_f32_e32 v9, 1.0, v10
	v_rcp_f32_e32 v9, v9
	v_add_f32_e32 v10, 1.0, v11
	v_rcp_f32_e32 v10, v10
	v_mul_f32_e32 v2, v2, v3
	v_mul_f32_e32 v3, v6, v9
	v_mul_f32_e32 v3, v3, v7
	v_mul_f32_e32 v4, v4, v10
	v_mul_f32_e32 v4, v4, v5
	v_cvt_pk_bf16_f32 v2, v8, v2
	v_cvt_pk_bf16_f32 v3, v3, v4
	global_store_dwordx2 v[130:131], v[2:3], off offset:8
	s_mov_b64 s[10:11], -1
	s_cbranch_vccnz .LBB0_1868
	s_andn2_b64 vcc, exec, s[0:1]
	s_cbranch_vccnz .LBB0_1867
	s_barrier
	s_branch .LBB0_1867
